# norm phases 4/9/12/15 context-slab path: 16 serialized slice-load round trips per context row replaced by 4 (all 10 loads of a chunk in flight together, same addition order)
# baseline (speedup 1.0000x reference)
; #define GAS __attribute__((address_space(1)))
; __device__ __forceinline__ void norm_phase(bool from_input, int gw, int NGW, int lane_in, float* H, const float* x_in, const float* c_in, const float* gain, const float* modL, int js, int jc, bf16* XN, ...
;     ...
;         if (pend) {
; #pragma unroll
;             for (int j = 0; j < 4; ++j) { const int c0 = 8 * (lane + 64 * j); f32x4 a0 = {0.f, 0.f, 0.f, 0.f}, a1 = a0;
;                 for (int qs = 0; qs < nsl; ++qs) { const GAS f32x4* sp = (const GAS f32x4*)(SLAB + ((size_t)qs * 512 + b * 256 + s) * 2048 + c0); a0 += sp[0]; a1 += sp[1]; }
;                 const f32x4 g0 = *(const f32x4*)(sgate + c0) * scoef, g1 = *(const f32x4*)(sgate + c0 + 4) * scoef;
; #pragma unroll
;                 for (int q = 0; q < 4; ++q) { v[j][q] += g0[q] * a0[q]; v[j][4 + q] += g1[q] * a1[q]; } }
.LBB0_472:
	s_lshl_b32 s0, s33, 8
	s_or_b32 s0, s0, s44
	s_mov_b32 s1, s35
	s_lshl_b64 s[0:1], s[0:1], 13
	s_waitcnt vmcnt(0)
	v_lshl_add_u64 v[206:207], v[92:93], 0, s[0:1]
	v_lshl_add_u64 v[210:211], v[92:93], 0, s[0:1]
	v_lshl_add_u64 v[210:211], v[210:211], 0, s[38:39]
	v_lshl_add_u64 v[214:215], v[92:93], 0, s[0:1]
	v_lshl_add_u64 v[214:215], v[214:215], 0, s[40:41]
	v_lshl_add_u64 v[218:219], v[92:93], 0, s[0:1]
	v_lshl_add_u64 v[218:219], v[218:219], 0, s[42:43]
	v_lshl_add_u64 v[226:227], v[92:93], 0, s[0:1]
	v_lshl_add_u64 v[230:231], v[92:93], 0, s[0:1]
	v_add_co_u32_e32 v230, vcc, s6, v230
	s_nop 1
	v_addc_co_u32_e32 v231, vcc, 0, v231, vcc
	v_lshl_add_u64 v[234:235], v[92:93], 0, s[0:1]
	v_add_co_u32_e32 v234, vcc, s7, v234
	s_nop 1
	v_addc_co_u32_e32 v235, vcc, 0, v235, vcc
	v_lshl_add_u64 v[238:239], v[92:93], 0, s[0:1]
	v_add_co_u32_e32 v238, vcc, s8, v238
	s_nop 1
	v_addc_co_u32_e32 v239, vcc, 0, v239, vcc
	global_load_dwordx4 v[206:209], v[206:207], off offset:16
	global_load_dwordx4 v[210:213], v[210:211], off offset:16
	global_load_dwordx4 v[214:217], v[214:215], off offset:16
	global_load_dwordx4 v[218:221], v[218:219], off offset:16
	global_load_dwordx4 v[222:225], v[94:95], off offset:16
	global_load_dwordx4 v[226:229], v[226:227], off
	global_load_dwordx4 v[230:233], v[230:231], off
	global_load_dwordx4 v[234:237], v[234:235], off
	global_load_dwordx4 v[238:241], v[238:239], off
	global_load_dwordx4 v[242:245], v[94:95], off
	s_waitcnt vmcnt(0)
	v_pk_add_f32 v[206:207], v[206:207], 0 op_sel_hi:[1,0]
	s_nop 0
	v_pk_add_f32 v[206:207], v[206:207], v[210:211]
	v_pk_add_f32 v[206:207], v[206:207], v[214:215]
	v_pk_add_f32 v[206:207], v[206:207], v[218:219]
	v_pk_mul_f32 v[222:223], v[222:223], 0.5 op_sel_hi:[1,0]
	s_nop 0
	v_pk_fma_f32 v[56:57], v[206:207], v[222:223], v[56:57]
	v_pk_add_f32 v[226:227], v[226:227], 0 op_sel_hi:[1,0]
	s_nop 0
	v_pk_add_f32 v[226:227], v[226:227], v[230:231]
	v_pk_add_f32 v[226:227], v[226:227], v[234:235]
	v_pk_add_f32 v[226:227], v[226:227], v[238:239]
	v_pk_mul_f32 v[242:243], v[242:243], 0.5 op_sel_hi:[1,0]
	s_nop 0
	v_pk_fma_f32 v[60:61], v[226:227], v[242:243], v[60:61]
	v_pk_add_f32 v[228:229], v[228:229], 0 op_sel_hi:[1,0]
	s_nop 0
	v_pk_add_f32 v[228:229], v[228:229], v[232:233]
	v_pk_add_f32 v[228:229], v[228:229], v[236:237]
	v_pk_add_f32 v[228:229], v[228:229], v[240:241]
	v_pk_mul_f32 v[244:245], v[244:245], 0.5 op_sel_hi:[1,0]
	s_nop 0
	v_pk_fma_f32 v[62:63], v[228:229], v[244:245], v[62:63]
	v_pk_add_f32 v[208:209], v[208:209], 0 op_sel_hi:[1,0]
	s_nop 0
	v_pk_add_f32 v[208:209], v[208:209], v[212:213]
	v_pk_add_f32 v[208:209], v[208:209], v[216:217]
	v_pk_add_f32 v[208:209], v[208:209], v[220:221]
	v_pk_mul_f32 v[224:225], v[224:225], 0.5 op_sel_hi:[1,0]
	s_nop 0
	v_pk_fma_f32 v[58:59], v[208:209], v[224:225], v[58:59]
	v_lshl_add_u64 v[206:207], v[106:107], 0, s[0:1]
	v_lshl_add_u64 v[210:211], v[106:107], 0, s[0:1]
	v_lshl_add_u64 v[210:211], v[210:211], 0, s[38:39]
	v_lshl_add_u64 v[214:215], v[106:107], 0, s[0:1]
	v_lshl_add_u64 v[214:215], v[214:215], 0, s[40:41]
	v_lshl_add_u64 v[218:219], v[106:107], 0, s[0:1]
	v_lshl_add_u64 v[218:219], v[218:219], 0, s[42:43]
	v_lshl_add_u64 v[226:227], v[106:107], 0, s[0:1]
	v_lshl_add_u64 v[230:231], v[106:107], 0, s[0:1]
	v_add_co_u32_e32 v230, vcc, s6, v230
	s_nop 1
	v_addc_co_u32_e32 v231, vcc, 0, v231, vcc
	v_lshl_add_u64 v[234:235], v[106:107], 0, s[0:1]
	v_add_co_u32_e32 v234, vcc, s7, v234
	s_nop 1
	v_addc_co_u32_e32 v235, vcc, 0, v235, vcc
	v_lshl_add_u64 v[238:239], v[106:107], 0, s[0:1]
	v_add_co_u32_e32 v238, vcc, s8, v238
	s_nop 1
	v_addc_co_u32_e32 v239, vcc, 0, v239, vcc
	global_load_dwordx4 v[206:209], v[206:207], off offset:16
	global_load_dwordx4 v[210:213], v[210:211], off offset:16
	global_load_dwordx4 v[214:217], v[214:215], off offset:16
	global_load_dwordx4 v[218:221], v[218:219], off offset:16
	global_load_dwordx4 v[222:225], v[96:97], off offset:16
	global_load_dwordx4 v[226:229], v[226:227], off
	global_load_dwordx4 v[230:233], v[230:231], off
	global_load_dwordx4 v[234:237], v[234:235], off
	global_load_dwordx4 v[238:241], v[238:239], off
	global_load_dwordx4 v[242:245], v[96:97], off
	s_waitcnt vmcnt(0)
	v_pk_add_f32 v[206:207], v[206:207], 0 op_sel_hi:[1,0]
	s_nop 0
	v_pk_add_f32 v[206:207], v[206:207], v[210:211]
	v_pk_add_f32 v[206:207], v[206:207], v[214:215]
	v_pk_add_f32 v[206:207], v[206:207], v[218:219]
	v_pk_mul_f32 v[222:223], v[222:223], 0.5 op_sel_hi:[1,0]
	s_nop 0
	v_pk_fma_f32 v[48:49], v[206:207], v[222:223], v[48:49]
	v_pk_add_f32 v[226:227], v[226:227], 0 op_sel_hi:[1,0]
	s_nop 0
	v_pk_add_f32 v[226:227], v[226:227], v[230:231]
	v_pk_add_f32 v[226:227], v[226:227], v[234:235]
	v_pk_add_f32 v[226:227], v[226:227], v[238:239]
	v_pk_mul_f32 v[242:243], v[242:243], 0.5 op_sel_hi:[1,0]
	s_nop 0
	v_pk_fma_f32 v[52:53], v[226:227], v[242:243], v[52:53]
	v_pk_add_f32 v[228:229], v[228:229], 0 op_sel_hi:[1,0]
	s_nop 0
	v_pk_add_f32 v[228:229], v[228:229], v[232:233]
	v_pk_add_f32 v[228:229], v[228:229], v[236:237]
	v_pk_add_f32 v[228:229], v[228:229], v[240:241]
	v_pk_mul_f32 v[244:245], v[244:245], 0.5 op_sel_hi:[1,0]
	s_nop 0
	v_pk_fma_f32 v[54:55], v[228:229], v[244:245], v[54:55]
	v_pk_add_f32 v[208:209], v[208:209], 0 op_sel_hi:[1,0]
	s_nop 0
	v_pk_add_f32 v[208:209], v[208:209], v[212:213]
	v_pk_add_f32 v[208:209], v[208:209], v[216:217]
	v_pk_add_f32 v[208:209], v[208:209], v[220:221]
	v_pk_mul_f32 v[224:225], v[224:225], 0.5 op_sel_hi:[1,0]
	s_nop 0
	v_pk_fma_f32 v[50:51], v[208:209], v[224:225], v[50:51]
	v_lshl_add_u64 v[206:207], v[98:99], 0, s[0:1]
	v_lshl_add_u64 v[210:211], v[98:99], 0, s[0:1]
	v_add_co_u32_e32 v210, vcc, s6, v210
	s_nop 1
	v_addc_co_u32_e32 v211, vcc, 0, v211, vcc
	v_lshl_add_u64 v[214:215], v[98:99], 0, s[0:1]
	v_add_co_u32_e32 v214, vcc, s7, v214
	s_nop 1
	v_addc_co_u32_e32 v215, vcc, 0, v215, vcc
	v_lshl_add_u64 v[218:219], v[98:99], 0, s[0:1]
	v_add_co_u32_e32 v218, vcc, s8, v218
	s_nop 1
	v_addc_co_u32_e32 v219, vcc, 0, v219, vcc
	v_lshl_add_u64 v[226:227], v[98:99], 0, s[0:1]
	v_lshl_add_u64 v[230:231], v[98:99], 0, s[0:1]
	v_lshl_add_u64 v[230:231], v[230:231], 0, s[38:39]
	v_lshl_add_u64 v[234:235], v[98:99], 0, s[0:1]
	v_lshl_add_u64 v[234:235], v[234:235], 0, s[40:41]
	v_lshl_add_u64 v[238:239], v[98:99], 0, s[0:1]
	v_lshl_add_u64 v[238:239], v[238:239], 0, s[42:43]
	global_load_dwordx4 v[206:209], v[206:207], off
	global_load_dwordx4 v[210:213], v[210:211], off
	global_load_dwordx4 v[214:217], v[214:215], off
	global_load_dwordx4 v[218:221], v[218:219], off
	global_load_dwordx4 v[222:225], v[100:101], off
	global_load_dwordx4 v[226:229], v[226:227], off offset:16
	global_load_dwordx4 v[230:233], v[230:231], off offset:16
	global_load_dwordx4 v[234:237], v[234:235], off offset:16
	global_load_dwordx4 v[238:241], v[238:239], off offset:16
	global_load_dwordx4 v[242:245], v[100:101], off offset:16
	s_waitcnt vmcnt(0)
; #define GAS __attribute__((address_space(1)))
; __device__ __forceinline__ void norm_phase(bool from_input, int gw, int NGW, int lane_in, float* H, const float* x_in, const float* c_in, const float* gain, const float* modL, int js, int jc, bf16* XN, ...
;     ...
;         if (pend) {
; #pragma unroll
;             for (int j = 0; j < 4; ++j) { const int c0 = 8 * (lane + 64 * j); f32x4 a0 = {0.f, 0.f, 0.f, 0.f}, a1 = a0;
;                 for (int qs = 0; qs < nsl; ++qs) { const GAS f32x4* sp = (const GAS f32x4*)(SLAB + ((size_t)qs * 512 + b * 256 + s) * 2048 + c0); a0 += sp[0]; a1 += sp[1]; }
;                 const f32x4 g0 = *(const f32x4*)(sgate + c0) * scoef, g1 = *(const f32x4*)(sgate + c0 + 4) * scoef;
; #pragma unroll
;                 for (int q = 0; q < 4; ++q) { v[j][q] += g0[q] * a0[q]; v[j][4 + q] += g1[q] * a1[q]; } }
	v_pk_add_f32 v[206:207], v[206:207], 0 op_sel_hi:[1,0]
	s_nop 0
	v_pk_add_f32 v[206:207], v[206:207], v[210:211]
	v_pk_add_f32 v[206:207], v[206:207], v[214:215]
	v_pk_add_f32 v[206:207], v[206:207], v[218:219]
	v_pk_mul_f32 v[222:223], v[222:223], 0.5 op_sel_hi:[1,0]
	s_nop 0
	v_pk_fma_f32 v[44:45], v[206:207], v[222:223], v[44:45]
	v_pk_add_f32 v[226:227], v[226:227], 0 op_sel_hi:[1,0]
	s_nop 0
	v_pk_add_f32 v[226:227], v[226:227], v[230:231]
	v_pk_add_f32 v[226:227], v[226:227], v[234:235]
	v_pk_add_f32 v[226:227], v[226:227], v[238:239]
	v_pk_mul_f32 v[242:243], v[242:243], 0.5 op_sel_hi:[1,0]
	s_nop 0
	v_pk_fma_f32 v[40:41], v[226:227], v[242:243], v[40:41]
	v_pk_add_f32 v[208:209], v[208:209], 0 op_sel_hi:[1,0]
	s_nop 0
	v_pk_add_f32 v[208:209], v[208:209], v[212:213]
	v_pk_add_f32 v[208:209], v[208:209], v[216:217]
	v_pk_add_f32 v[208:209], v[208:209], v[220:221]
	v_pk_mul_f32 v[224:225], v[224:225], 0.5 op_sel_hi:[1,0]
	s_nop 0
	v_pk_fma_f32 v[46:47], v[208:209], v[224:225], v[46:47]
	v_pk_add_f32 v[228:229], v[228:229], 0 op_sel_hi:[1,0]
	s_nop 0
	v_pk_add_f32 v[228:229], v[228:229], v[232:233]
	v_pk_add_f32 v[228:229], v[228:229], v[236:237]
	v_pk_add_f32 v[228:229], v[228:229], v[240:241]
	v_pk_mul_f32 v[244:245], v[244:245], 0.5 op_sel_hi:[1,0]
	s_nop 0
	v_pk_fma_f32 v[42:43], v[228:229], v[244:245], v[42:43]
	v_lshl_add_u64 v[206:207], v[102:103], 0, s[0:1]
	v_lshl_add_u64 v[210:211], v[102:103], 0, s[0:1]
	v_lshl_add_u64 v[210:211], v[210:211], 0, s[38:39]
	v_lshl_add_u64 v[214:215], v[102:103], 0, s[0:1]
	v_lshl_add_u64 v[214:215], v[214:215], 0, s[40:41]
	v_lshl_add_u64 v[218:219], v[102:103], 0, s[0:1]
	v_lshl_add_u64 v[218:219], v[218:219], 0, s[42:43]
	v_lshl_add_u64 v[226:227], v[102:103], 0, s[0:1]
	v_lshl_add_u64 v[230:231], v[102:103], 0, s[0:1]
	v_add_co_u32_e32 v230, vcc, s6, v230
	s_nop 1
	v_addc_co_u32_e32 v231, vcc, 0, v231, vcc
	v_lshl_add_u64 v[234:235], v[102:103], 0, s[0:1]
	v_add_co_u32_e32 v234, vcc, s7, v234
	s_nop 1
	v_addc_co_u32_e32 v235, vcc, 0, v235, vcc
	v_lshl_add_u64 v[238:239], v[102:103], 0, s[0:1]
	v_add_co_u32_e32 v238, vcc, s8, v238
	s_nop 1
	v_addc_co_u32_e32 v239, vcc, 0, v239, vcc
	global_load_dwordx4 v[206:209], v[206:207], off offset:16
	global_load_dwordx4 v[210:213], v[210:211], off offset:16
	global_load_dwordx4 v[214:217], v[214:215], off offset:16
	global_load_dwordx4 v[218:221], v[218:219], off offset:16
	global_load_dwordx4 v[222:225], v[104:105], off offset:16
	global_load_dwordx4 v[226:229], v[226:227], off
	global_load_dwordx4 v[230:233], v[230:231], off
	global_load_dwordx4 v[234:237], v[234:235], off
	global_load_dwordx4 v[238:241], v[238:239], off
	global_load_dwordx4 v[242:245], v[104:105], off
	s_waitcnt vmcnt(0)
; #define GAS __attribute__((address_space(1)))
; __device__ __forceinline__ void h24_store(unsigned char* Hb, size_t r, int lane, const float (&v)[4][8]) {
; #pragma unroll
;     for (int j = 0; j < 4; ++j) { const size_t e = r * 2048 + 8 * (lane + 64 * j); unsigned u[8];
; #pragma unroll
;         for (int q = 0; q < 8; ++q) u[q] = __builtin_bit_cast(unsigned, v[j][q]) + 0x800u;
;         v4u hi; unsigned lo = 0u;
; #pragma unroll
;         for (int q = 0; q < 4; ++q) hi[q] = (u[2 * q] >> 16) | (u[2 * q + 1] & 0xffff0000u);
; #pragma unroll
;         for (int q = 0; q < 8; ++q) lo |= ((u[q] >> 12) & 0xfu) << (4 * q);
;         __builtin_nontemporal_store(hi, (GAS v4u*)(Hb + e * 2)); __builtin_nontemporal_store(lo, (GAS unsigned*)(Hb + H_LO_OFF + (e >> 1))); }
; __device__ __forceinline__ void norm_phase(bool from_input, int gw, int NGW, int lane_in, float* H, const float* x_in, const float* c_in, const float* gain, const float* modL, int js, int jc, bf16* XN, ...
;     ...
;             for (int j = 0; j < 4; ++j) { const int c0 = 8 * (lane + 64 * j); f32x4 a0 = {0.f, 0.f, 0.f, 0.f}, a1 = a0;
;                 for (int qs = 0; qs < nsl; ++qs) { const GAS f32x4* sp = (const GAS f32x4*)(SLAB + ((size_t)qs * 512 + b * 256 + s) * 2048 + c0); a0 += sp[0]; a1 += sp[1]; }
;                 const f32x4 g0 = *(const f32x4*)(sgate + c0) * scoef, g1 = *(const f32x4*)(sgate + c0 + 4) * scoef;
; #pragma unroll
;                 for (int q = 0; q < 4; ++q) { v[j][q] += g0[q] * a0[q]; v[j][4 + q] += g1[q] * a1[q]; } }
	v_pk_add_f32 v[206:207], v[206:207], 0 op_sel_hi:[1,0]
	s_nop 0
	v_pk_add_f32 v[206:207], v[206:207], v[210:211]
	v_pk_add_f32 v[206:207], v[206:207], v[214:215]
	v_pk_add_f32 v[206:207], v[206:207], v[218:219]
	v_pk_mul_f32 v[222:223], v[222:223], 0.5 op_sel_hi:[1,0]
	s_nop 0
	v_pk_fma_f32 v[32:33], v[206:207], v[222:223], v[32:33]
	v_pk_add_f32 v[226:227], v[226:227], 0 op_sel_hi:[1,0]
	s_nop 0
	v_pk_add_f32 v[226:227], v[226:227], v[230:231]
	v_pk_add_f32 v[226:227], v[226:227], v[234:235]
	v_pk_add_f32 v[226:227], v[226:227], v[238:239]
	v_pk_mul_f32 v[242:243], v[242:243], 0.5 op_sel_hi:[1,0]
	s_nop 0
	v_pk_fma_f32 v[36:37], v[226:227], v[242:243], v[36:37]
	v_pk_add_f32 v[228:229], v[228:229], 0 op_sel_hi:[1,0]
	s_nop 0
	v_pk_add_f32 v[228:229], v[228:229], v[232:233]
	v_pk_add_f32 v[228:229], v[228:229], v[236:237]
	v_pk_add_f32 v[228:229], v[228:229], v[240:241]
	v_pk_mul_f32 v[244:245], v[244:245], 0.5 op_sel_hi:[1,0]
	s_nop 0
	v_pk_fma_f32 v[38:39], v[228:229], v[244:245], v[38:39]
	v_pk_add_f32 v[208:209], v[208:209], 0 op_sel_hi:[1,0]
	s_nop 0
	v_pk_add_f32 v[208:209], v[208:209], v[212:213]
	v_pk_add_f32 v[208:209], v[208:209], v[216:217]
	v_pk_add_f32 v[208:209], v[208:209], v[220:221]
	v_pk_mul_f32 v[224:225], v[224:225], 0.5 op_sel_hi:[1,0]
	s_nop 0
	v_pk_fma_f32 v[34:35], v[208:209], v[224:225], v[34:35]
	v_add_u32_e32 v79, 0x800, v56
	v_add_u32_e32 v74, 0x800, v58
	v_add_u32_e32 v81, 0x800, v59
	s_lshl_b64 s[0:1], s[34:35], 11
	v_add_u32_e32 v68, 0x800, v62
	v_add_u32_e32 v69, 0x800, v60
	v_add_u32_e32 v70, 0x800, v63
	v_add_u32_e32 v71, 0x800, v61
	v_lshrrev_b32_e32 v64, 16, v68
	v_lshrrev_b32_e32 v66, 16, v69
	v_add_u32_e32 v142, 0x800, v57
	v_lshrrev_b32_e32 v143, 16, v79
	v_and_or_b32 v65, v70, s3, v64
	v_and_or_b32 v64, v71, s3, v66
	v_lshrrev_b32_e32 v69, 12, v69
	v_lshrrev_b32_e32 v71, 8, v71
	v_lshrrev_b32_e32 v68, 4, v68
	v_and_b32_e32 v70, 0xf000, v70
	v_lshrrev_b32_e32 v67, 16, v74
	v_and_or_b32 v66, v142, s3, v143
	v_and_b32_e32 v71, 0xf0, v71
	v_and_b32_e32 v68, 0xf00, v68
	v_lshlrev_b32_e32 v79, 4, v79
	v_lshlrev_b32_e32 v142, 8, v142
	v_and_or_b32 v69, v69, 15, v70
	v_and_or_b32 v67, v81, s3, v67
	v_and_b32_e32 v79, 0xf0000, v79
	v_and_b32_e32 v142, 0xf00000, v142
	v_lshlrev_b32_e32 v74, 12, v74
	v_lshlrev_b32_e32 v81, 16, v81
	v_or3_b32 v68, v69, v71, v68
	v_and_b32_e32 v74, 0xf000000, v74
	v_and_b32_e32 v81, 0xf0000000, v81
	v_or3_b32 v68, v68, v79, v142
	v_or3_b32 v74, v68, v74, v81
	v_mov_b32_e32 v69, s1
	v_or_b32_e32 v68, s0, v72
	v_lshl_add_u64 v[70:71], v[68:69], 1, s[90:91]
	global_store_dwordx4 v[70:71], v[64:67], off nt
	v_add_u32_e32 v70, 0x800, v55
	v_add_u32_e32 v71, 0x800, v53
	v_lshrrev_b64 v[64:65], 1, v[68:69]
	v_lshl_add_u64 v[64:65], s[78:79], 0, v[64:65]
	v_add_u32_e32 v68, 0x800, v54
	v_add_u32_e32 v69, 0x800, v52
	global_store_dword v[64:65], v74, off nt
	v_add_u32_e32 v79, 0x800, v48
	v_lshrrev_b32_e32 v64, 16, v68
	v_lshrrev_b32_e32 v66, 16, v69
	v_add_u32_e32 v74, 0x800, v50
	v_add_u32_e32 v142, 0x800, v49
	v_lshrrev_b32_e32 v143, 16, v79
	v_and_or_b32 v65, v70, s3, v64
	v_and_or_b32 v64, v71, s3, v66
	v_lshrrev_b32_e32 v69, 12, v69
	v_lshrrev_b32_e32 v71, 8, v71
	v_lshrrev_b32_e32 v68, 4, v68
	v_and_b32_e32 v70, 0xf000, v70
	v_add_u32_e32 v81, 0x800, v51
	v_lshrrev_b32_e32 v67, 16, v74
	v_and_or_b32 v66, v142, s3, v143
	v_and_b32_e32 v71, 0xf0, v71
	v_and_b32_e32 v68, 0xf00, v68
	v_lshlrev_b32_e32 v79, 4, v79
	v_lshlrev_b32_e32 v142, 8, v142
	v_and_or_b32 v69, v69, 15, v70
	v_and_or_b32 v67, v81, s3, v67
	v_and_b32_e32 v79, 0xf0000, v79
	v_and_b32_e32 v142, 0xf00000, v142
	v_lshlrev_b32_e32 v74, 12, v74
	v_lshlrev_b32_e32 v81, 16, v81
	v_or3_b32 v68, v69, v71, v68
	v_and_b32_e32 v74, 0xf000000, v74
	v_and_b32_e32 v81, 0xf0000000, v81
	v_or3_b32 v68, v68, v79, v142
	v_or3_b32 v74, v68, v74, v81
	v_mov_b32_e32 v69, s1
	v_or_b32_e32 v68, s0, v76
	v_lshl_add_u64 v[70:71], v[68:69], 1, s[90:91]
	global_store_dwordx4 v[70:71], v[64:67], off nt
	v_add_u32_e32 v70, 0x800, v47
	v_add_u32_e32 v71, 0x800, v45
	v_lshrrev_b64 v[64:65], 1, v[68:69]
	v_lshl_add_u64 v[64:65], s[78:79], 0, v[64:65]
	v_add_u32_e32 v68, 0x800, v46
	v_add_u32_e32 v69, 0x800, v44
	global_store_dword v[64:65], v74, off nt
	v_add_u32_e32 v79, 0x800, v40
	v_lshrrev_b32_e32 v64, 16, v68
	v_lshrrev_b32_e32 v66, 16, v69
	v_add_u32_e32 v74, 0x800, v42
	v_add_u32_e32 v142, 0x800, v41
	v_lshrrev_b32_e32 v143, 16, v79
	v_and_or_b32 v65, v70, s3, v64
	v_and_or_b32 v64, v71, s3, v66
	v_lshrrev_b32_e32 v69, 12, v69
	v_lshrrev_b32_e32 v71, 8, v71
	v_lshrrev_b32_e32 v68, 4, v68
	v_and_b32_e32 v70, 0xf000, v70
	v_add_u32_e32 v81, 0x800, v43
	v_lshrrev_b32_e32 v67, 16, v74
	v_and_or_b32 v66, v142, s3, v143
	v_and_b32_e32 v71, 0xf0, v71
	v_and_b32_e32 v68, 0xf00, v68
	v_lshlrev_b32_e32 v79, 4, v79
	v_lshlrev_b32_e32 v142, 8, v142
	v_and_or_b32 v69, v69, 15, v70
	v_and_or_b32 v67, v81, s3, v67
	v_and_b32_e32 v79, 0xf0000, v79
	v_and_b32_e32 v142, 0xf00000, v142
	v_lshlrev_b32_e32 v74, 12, v74
	v_lshlrev_b32_e32 v81, 16, v81
	v_or3_b32 v68, v69, v71, v68
	v_and_b32_e32 v74, 0xf000000, v74
	v_and_b32_e32 v81, 0xf0000000, v81
	v_or3_b32 v68, v68, v79, v142
	v_or3_b32 v74, v68, v74, v81
	v_mov_b32_e32 v69, s1
	v_or_b32_e32 v68, s0, v78
	v_lshl_add_u64 v[70:71], v[68:69], 1, s[90:91]
	global_store_dwordx4 v[70:71], v[64:67], off nt
	v_add_u32_e32 v70, 0x800, v39
	v_add_u32_e32 v71, 0x800, v37
	v_lshrrev_b64 v[64:65], 1, v[68:69]
	v_lshl_add_u64 v[64:65], s[78:79], 0, v[64:65]
	v_add_u32_e32 v68, 0x800, v38
	v_add_u32_e32 v69, 0x800, v36
	global_store_dword v[64:65], v74, off nt
	v_add_u32_e32 v79, 0x800, v32
	v_lshrrev_b32_e32 v64, 16, v68
	v_lshrrev_b32_e32 v66, 16, v69
	v_add_u32_e32 v74, 0x800, v34
	v_add_u32_e32 v142, 0x800, v33
	v_lshrrev_b32_e32 v143, 16, v79
	v_and_or_b32 v65, v70, s3, v64
	v_and_or_b32 v64, v71, s3, v66
	v_lshrrev_b32_e32 v69, 12, v69
	v_lshrrev_b32_e32 v71, 8, v71
	v_lshrrev_b32_e32 v68, 4, v68
	v_and_b32_e32 v70, 0xf000, v70
	v_add_u32_e32 v81, 0x800, v35
	v_lshrrev_b32_e32 v67, 16, v74
	v_and_or_b32 v66, v142, s3, v143
	v_and_b32_e32 v71, 0xf0, v71
	v_and_b32_e32 v68, 0xf00, v68
	v_lshlrev_b32_e32 v79, 4, v79
	v_lshlrev_b32_e32 v142, 8, v142
	v_and_or_b32 v69, v69, 15, v70
	v_and_or_b32 v67, v81, s3, v67
	v_and_b32_e32 v79, 0xf0000, v79
	v_and_b32_e32 v142, 0xf00000, v142
	v_lshlrev_b32_e32 v74, 12, v74
	v_lshlrev_b32_e32 v81, 16, v81
	v_or3_b32 v68, v69, v71, v68
	v_and_b32_e32 v74, 0xf000000, v74
	v_and_b32_e32 v81, 0xf0000000, v81
	v_or3_b32 v68, v68, v79, v142
	v_or3_b32 v74, v68, v74, v81
	v_mov_b32_e32 v69, s1
	v_or_b32_e32 v68, s0, v80
	v_lshl_add_u64 v[70:71], v[68:69], 1, s[90:91]
	global_store_dwordx4 v[70:71], v[64:67], off nt
	s_nop 1
	s_nop 1
	v_lshrrev_b64 v[64:65], 1, v[68:69]
	v_lshl_add_u64 v[64:65], s[78:79], 0, v[64:65]
	global_store_dword v[64:65], v74, off nt

; #define GAS __attribute__((address_space(1)))
; __device__ __forceinline__ void norm_phase(bool from_input, int gw, int NGW, int lane_in, float* H, const float* x_in, const float* c_in, const float* gain, const float* modL, int js, int jc, bf16* XN, ...
;     ...
;         if (pend) {
; #pragma unroll
;             for (int j = 0; j < 4; ++j) { const int c0 = 8 * (lane + 64 * j); f32x4 a0 = {0.f, 0.f, 0.f, 0.f}, a1 = a0;
;                 for (int qs = 0; qs < nsl; ++qs) { const GAS f32x4* sp = (const GAS f32x4*)(SLAB + ((size_t)qs * 512 + b * 256 + s) * 2048 + c0); a0 += sp[0]; a1 += sp[1]; }
;                 const f32x4 g0 = *(const f32x4*)(sgate + c0) * scoef, g1 = *(const f32x4*)(sgate + c0 + 4) * scoef;
; #pragma unroll
;                 for (int q = 0; q < 4; ++q) { v[j][q] += g0[q] * a0[q]; v[j][4 + q] += g1[q] * a1[q]; } }
.LBB0_1138:
	s_andn2_b64 vcc, exec, s[0:1]
	s_cbranch_vccnz .LBB0_1129
	s_lshl_b32 s0, s10, 8
	s_or_b32 s0, s0, s11
	s_mov_b32 s1, s21
	s_lshl_b64 s[0:1], s[0:1], 13
	s_waitcnt vmcnt(0)
	v_lshl_add_u64 v[206:207], v[58:59], 0, s[0:1]
	v_lshl_add_u64 v[210:211], v[58:59], 0, s[0:1]
	v_lshl_add_u64 v[210:211], v[210:211], 0, s[42:43]
	v_lshl_add_u64 v[214:215], v[58:59], 0, s[0:1]
	v_lshl_add_u64 v[214:215], v[214:215], 0, s[48:49]
	v_lshl_add_u64 v[218:219], v[58:59], 0, s[0:1]
	v_lshl_add_u64 v[218:219], v[218:219], 0, s[54:55]
	v_lshl_add_u64 v[226:227], v[58:59], 0, s[0:1]
	v_lshl_add_u64 v[230:231], v[58:59], 0, s[0:1]
	v_add_co_u32_e32 v230, vcc, s6, v230
	s_nop 1
	v_addc_co_u32_e32 v231, vcc, 0, v231, vcc
	v_lshl_add_u64 v[234:235], v[58:59], 0, s[0:1]
	v_add_co_u32_e32 v234, vcc, s7, v234
	s_nop 1
	v_addc_co_u32_e32 v235, vcc, 0, v235, vcc
	v_lshl_add_u64 v[238:239], v[58:59], 0, s[0:1]
	v_add_co_u32_e32 v238, vcc, s8, v238
	s_nop 1
	v_addc_co_u32_e32 v239, vcc, 0, v239, vcc
	global_load_dwordx4 v[206:209], v[206:207], off offset:16
	global_load_dwordx4 v[210:213], v[210:211], off offset:16
	global_load_dwordx4 v[214:217], v[214:215], off offset:16
	global_load_dwordx4 v[218:221], v[218:219], off offset:16
	global_load_dwordx4 v[222:225], v[60:61], off offset:16
	global_load_dwordx4 v[226:229], v[226:227], off
	global_load_dwordx4 v[230:233], v[230:231], off
	global_load_dwordx4 v[234:237], v[234:235], off
	global_load_dwordx4 v[238:241], v[238:239], off
	global_load_dwordx4 v[242:245], v[60:61], off
	s_waitcnt vmcnt(0)
	v_pk_add_f32 v[206:207], v[206:207], 0 op_sel_hi:[1,0]
	s_nop 0
	v_pk_add_f32 v[206:207], v[206:207], v[210:211]
	v_pk_add_f32 v[206:207], v[206:207], v[214:215]
	v_pk_add_f32 v[206:207], v[206:207], v[218:219]
	v_pk_fma_f32 v[112:113], v[206:207], v[222:223], v[112:113]
	v_pk_add_f32 v[226:227], v[226:227], 0 op_sel_hi:[1,0]
	s_nop 0
	v_pk_add_f32 v[226:227], v[226:227], v[230:231]
	v_pk_add_f32 v[226:227], v[226:227], v[234:235]
	v_pk_add_f32 v[226:227], v[226:227], v[238:239]
	v_pk_fma_f32 v[108:109], v[226:227], v[242:243], v[108:109]
	v_pk_add_f32 v[228:229], v[228:229], 0 op_sel_hi:[1,0]
	s_nop 0
	v_pk_add_f32 v[228:229], v[228:229], v[232:233]
	v_pk_add_f32 v[228:229], v[228:229], v[236:237]
	v_pk_add_f32 v[228:229], v[228:229], v[240:241]
	v_pk_fma_f32 v[110:111], v[228:229], v[244:245], v[110:111]
	v_pk_add_f32 v[208:209], v[208:209], 0 op_sel_hi:[1,0]
	s_nop 0
	v_pk_add_f32 v[208:209], v[208:209], v[212:213]
	v_pk_add_f32 v[208:209], v[208:209], v[216:217]
	v_pk_add_f32 v[208:209], v[208:209], v[220:221]
	v_pk_fma_f32 v[114:115], v[208:209], v[224:225], v[114:115]
	v_lshl_add_u64 v[206:207], v[72:73], 0, s[0:1]
	v_lshl_add_u64 v[210:211], v[72:73], 0, s[0:1]
	v_lshl_add_u64 v[210:211], v[210:211], 0, s[42:43]
	v_lshl_add_u64 v[214:215], v[72:73], 0, s[0:1]
	v_lshl_add_u64 v[214:215], v[214:215], 0, s[48:49]
	v_lshl_add_u64 v[218:219], v[72:73], 0, s[0:1]
	v_lshl_add_u64 v[218:219], v[218:219], 0, s[54:55]
	v_lshl_add_u64 v[226:227], v[72:73], 0, s[0:1]
	v_lshl_add_u64 v[230:231], v[72:73], 0, s[0:1]
	v_add_co_u32_e32 v230, vcc, s6, v230
	s_nop 1
	v_addc_co_u32_e32 v231, vcc, 0, v231, vcc
	v_lshl_add_u64 v[234:235], v[72:73], 0, s[0:1]
	v_add_co_u32_e32 v234, vcc, s7, v234
	s_nop 1
	v_addc_co_u32_e32 v235, vcc, 0, v235, vcc
	v_lshl_add_u64 v[238:239], v[72:73], 0, s[0:1]
	v_add_co_u32_e32 v238, vcc, s8, v238
	s_nop 1
	v_addc_co_u32_e32 v239, vcc, 0, v239, vcc
	global_load_dwordx4 v[206:209], v[206:207], off offset:16
	global_load_dwordx4 v[210:213], v[210:211], off offset:16
	global_load_dwordx4 v[214:217], v[214:215], off offset:16
	global_load_dwordx4 v[218:221], v[218:219], off offset:16
	global_load_dwordx4 v[222:225], v[62:63], off offset:16
	global_load_dwordx4 v[226:229], v[226:227], off
	global_load_dwordx4 v[230:233], v[230:231], off
	global_load_dwordx4 v[234:237], v[234:235], off
	global_load_dwordx4 v[238:241], v[238:239], off
	global_load_dwordx4 v[242:245], v[62:63], off
	s_waitcnt vmcnt(0)
	v_pk_add_f32 v[206:207], v[206:207], 0 op_sel_hi:[1,0]
	s_nop 0
	v_pk_add_f32 v[206:207], v[206:207], v[210:211]
	v_pk_add_f32 v[206:207], v[206:207], v[214:215]
	v_pk_add_f32 v[206:207], v[206:207], v[218:219]
	v_pk_fma_f32 v[120:121], v[206:207], v[222:223], v[120:121]
	v_pk_add_f32 v[226:227], v[226:227], 0 op_sel_hi:[1,0]
	s_nop 0
	v_pk_add_f32 v[226:227], v[226:227], v[230:231]
	v_pk_add_f32 v[226:227], v[226:227], v[234:235]
	v_pk_add_f32 v[226:227], v[226:227], v[238:239]
	v_pk_fma_f32 v[116:117], v[226:227], v[242:243], v[116:117]
	v_pk_add_f32 v[228:229], v[228:229], 0 op_sel_hi:[1,0]
	s_nop 0
	v_pk_add_f32 v[228:229], v[228:229], v[232:233]
	v_pk_add_f32 v[228:229], v[228:229], v[236:237]
	v_pk_add_f32 v[228:229], v[228:229], v[240:241]
	v_pk_fma_f32 v[118:119], v[228:229], v[244:245], v[118:119]
	v_pk_add_f32 v[208:209], v[208:209], 0 op_sel_hi:[1,0]
	s_nop 0
	v_pk_add_f32 v[208:209], v[208:209], v[212:213]
	v_pk_add_f32 v[208:209], v[208:209], v[216:217]
	v_pk_add_f32 v[208:209], v[208:209], v[220:221]
	v_pk_fma_f32 v[122:123], v[208:209], v[224:225], v[122:123]
	v_lshl_add_u64 v[206:207], v[64:65], 0, s[0:1]
	v_lshl_add_u64 v[210:211], v[64:65], 0, s[0:1]
	v_lshl_add_u64 v[210:211], v[210:211], 0, s[42:43]
	v_lshl_add_u64 v[214:215], v[64:65], 0, s[0:1]
	v_lshl_add_u64 v[214:215], v[214:215], 0, s[48:49]
	v_lshl_add_u64 v[218:219], v[64:65], 0, s[0:1]
	v_lshl_add_u64 v[218:219], v[218:219], 0, s[54:55]
	v_lshl_add_u64 v[226:227], v[64:65], 0, s[0:1]
	v_lshl_add_u64 v[230:231], v[64:65], 0, s[0:1]
	v_add_co_u32_e32 v230, vcc, s6, v230
	s_nop 1
	v_addc_co_u32_e32 v231, vcc, 0, v231, vcc
	v_lshl_add_u64 v[234:235], v[64:65], 0, s[0:1]
	v_add_co_u32_e32 v234, vcc, s7, v234
	s_nop 1
	v_addc_co_u32_e32 v235, vcc, 0, v235, vcc
	v_lshl_add_u64 v[238:239], v[64:65], 0, s[0:1]
	v_add_co_u32_e32 v238, vcc, s8, v238
	s_nop 1
	v_addc_co_u32_e32 v239, vcc, 0, v239, vcc
	global_load_dwordx4 v[206:209], v[206:207], off offset:16
	global_load_dwordx4 v[210:213], v[210:211], off offset:16
	global_load_dwordx4 v[214:217], v[214:215], off offset:16
	global_load_dwordx4 v[218:221], v[218:219], off offset:16
	global_load_dwordx4 v[222:225], v[66:67], off offset:16
	global_load_dwordx4 v[226:229], v[226:227], off
	global_load_dwordx4 v[230:233], v[230:231], off
	global_load_dwordx4 v[234:237], v[234:235], off
	global_load_dwordx4 v[238:241], v[238:239], off
	global_load_dwordx4 v[242:245], v[66:67], off
	s_waitcnt vmcnt(0)
; #define GAS __attribute__((address_space(1)))
; __device__ __forceinline__ void norm_phase(bool from_input, int gw, int NGW, int lane_in, float* H, const float* x_in, const float* c_in, const float* gain, const float* modL, int js, int jc, bf16* XN, ...
;     ...
;             for (int j = 0; j < 4; ++j) { const int c0 = 8 * (lane + 64 * j); f32x4 a0 = {0.f, 0.f, 0.f, 0.f}, a1 = a0;
;                 for (int qs = 0; qs < nsl; ++qs) { const GAS f32x4* sp = (const GAS f32x4*)(SLAB + ((size_t)qs * 512 + b * 256 + s) * 2048 + c0); a0 += sp[0]; a1 += sp[1]; }
;                 const f32x4 g0 = *(const f32x4*)(sgate + c0) * scoef, g1 = *(const f32x4*)(sgate + c0 + 4) * scoef;
; #pragma unroll
;                 for (int q = 0; q < 4; ++q) { v[j][q] += g0[q] * a0[q]; v[j][4 + q] += g1[q] * a1[q]; } }
	v_pk_add_f32 v[206:207], v[206:207], 0 op_sel_hi:[1,0]
	s_nop 0
	v_pk_add_f32 v[206:207], v[206:207], v[210:211]
	v_pk_add_f32 v[206:207], v[206:207], v[214:215]
	v_pk_add_f32 v[206:207], v[206:207], v[218:219]
	v_pk_fma_f32 v[132:133], v[206:207], v[222:223], v[132:133]
	v_pk_add_f32 v[226:227], v[226:227], 0 op_sel_hi:[1,0]
	s_nop 0
	v_pk_add_f32 v[226:227], v[226:227], v[230:231]
	v_pk_add_f32 v[226:227], v[226:227], v[234:235]
	v_pk_add_f32 v[226:227], v[226:227], v[238:239]
	v_pk_fma_f32 v[128:129], v[226:227], v[242:243], v[128:129]
	v_pk_add_f32 v[228:229], v[228:229], 0 op_sel_hi:[1,0]
	s_nop 0
	v_pk_add_f32 v[228:229], v[228:229], v[232:233]
	v_pk_add_f32 v[228:229], v[228:229], v[236:237]
	v_pk_add_f32 v[228:229], v[228:229], v[240:241]
	v_pk_fma_f32 v[130:131], v[228:229], v[244:245], v[130:131]
	v_pk_add_f32 v[208:209], v[208:209], 0 op_sel_hi:[1,0]
	s_nop 0
	v_pk_add_f32 v[208:209], v[208:209], v[212:213]
	v_pk_add_f32 v[208:209], v[208:209], v[216:217]
	v_pk_add_f32 v[208:209], v[208:209], v[220:221]
	v_pk_fma_f32 v[134:135], v[208:209], v[224:225], v[134:135]
	v_lshl_add_u64 v[206:207], v[68:69], 0, s[0:1]
	v_lshl_add_u64 v[210:211], v[68:69], 0, s[0:1]
	v_add_co_u32_e32 v210, vcc, s6, v210
	s_nop 1
	v_addc_co_u32_e32 v211, vcc, 0, v211, vcc
	v_lshl_add_u64 v[214:215], v[68:69], 0, s[0:1]
	v_add_co_u32_e32 v214, vcc, s7, v214
	s_nop 1
	v_addc_co_u32_e32 v215, vcc, 0, v215, vcc
	v_lshl_add_u64 v[218:219], v[68:69], 0, s[0:1]
	v_add_co_u32_e32 v218, vcc, s8, v218
	s_nop 1
	v_addc_co_u32_e32 v219, vcc, 0, v219, vcc
	v_lshl_add_u64 v[226:227], v[68:69], 0, s[0:1]
	v_lshl_add_u64 v[230:231], v[68:69], 0, s[0:1]
	v_lshl_add_u64 v[230:231], v[230:231], 0, s[42:43]
	v_lshl_add_u64 v[234:235], v[68:69], 0, s[0:1]
	v_lshl_add_u64 v[234:235], v[234:235], 0, s[48:49]
	v_lshl_add_u64 v[238:239], v[68:69], 0, s[0:1]
	v_lshl_add_u64 v[238:239], v[238:239], 0, s[54:55]
	global_load_dwordx4 v[206:209], v[206:207], off
	global_load_dwordx4 v[210:213], v[210:211], off
	global_load_dwordx4 v[214:217], v[214:215], off
	global_load_dwordx4 v[218:221], v[218:219], off
	global_load_dwordx4 v[222:225], v[70:71], off
	global_load_dwordx4 v[226:229], v[226:227], off offset:16
	global_load_dwordx4 v[230:233], v[230:231], off offset:16
	global_load_dwordx4 v[234:237], v[234:235], off offset:16
	global_load_dwordx4 v[238:241], v[238:239], off offset:16
	global_load_dwordx4 v[242:245], v[70:71], off offset:16
	s_waitcnt vmcnt(0)
; #define GAS __attribute__((address_space(1)))
; __device__ __forceinline__ void h24_store(unsigned char* Hb, size_t r, int lane, const float (&v)[4][8]) {
; #pragma unroll
;     for (int j = 0; j < 4; ++j) { const size_t e = r * 2048 + 8 * (lane + 64 * j); unsigned u[8];
; #pragma unroll
;         for (int q = 0; q < 8; ++q) u[q] = __builtin_bit_cast(unsigned, v[j][q]) + 0x800u;
;         v4u hi; unsigned lo = 0u;
; #pragma unroll
;         for (int q = 0; q < 4; ++q) hi[q] = (u[2 * q] >> 16) | (u[2 * q + 1] & 0xffff0000u);
; #pragma unroll
;         for (int q = 0; q < 8; ++q) lo |= ((u[q] >> 12) & 0xfu) << (4 * q);
;         __builtin_nontemporal_store(hi, (GAS v4u*)(Hb + e * 2)); __builtin_nontemporal_store(lo, (GAS unsigned*)(Hb + H_LO_OFF + (e >> 1))); }
; __device__ __forceinline__ void norm_phase(bool from_input, int gw, int NGW, int lane_in, float* H, const float* x_in, const float* c_in, const float* gain, const float* modL, int js, int jc, bf16* XN, ...
;     ...
;             for (int j = 0; j < 4; ++j) { const int c0 = 8 * (lane + 64 * j); f32x4 a0 = {0.f, 0.f, 0.f, 0.f}, a1 = a0;
;                 for (int qs = 0; qs < nsl; ++qs) { const GAS f32x4* sp = (const GAS f32x4*)(SLAB + ((size_t)qs * 512 + b * 256 + s) * 2048 + c0); a0 += sp[0]; a1 += sp[1]; }
;                 const f32x4 g0 = *(const f32x4*)(sgate + c0) * scoef, g1 = *(const f32x4*)(sgate + c0 + 4) * scoef;
; #pragma unroll
;                 for (int q = 0; q < 4; ++q) { v[j][q] += g0[q] * a0[q]; v[j][4 + q] += g1[q] * a1[q]; } }
	v_pk_add_f32 v[206:207], v[206:207], 0 op_sel_hi:[1,0]
	s_nop 0
	v_pk_add_f32 v[206:207], v[206:207], v[210:211]
	v_pk_add_f32 v[206:207], v[206:207], v[214:215]
	v_pk_add_f32 v[206:207], v[206:207], v[218:219]
	v_pk_fma_f32 v[148:149], v[206:207], v[222:223], v[148:149]
	v_pk_add_f32 v[226:227], v[226:227], 0 op_sel_hi:[1,0]
	s_nop 0
	v_pk_add_f32 v[226:227], v[226:227], v[230:231]
	v_pk_add_f32 v[226:227], v[226:227], v[234:235]
	v_pk_add_f32 v[226:227], v[226:227], v[238:239]
	v_pk_fma_f32 v[152:153], v[226:227], v[242:243], v[152:153]
	v_pk_add_f32 v[208:209], v[208:209], 0 op_sel_hi:[1,0]
	s_nop 0
	v_pk_add_f32 v[208:209], v[208:209], v[212:213]
	v_pk_add_f32 v[208:209], v[208:209], v[216:217]
	v_pk_add_f32 v[208:209], v[208:209], v[220:221]
	v_pk_fma_f32 v[150:151], v[208:209], v[224:225], v[150:151]
	v_pk_add_f32 v[228:229], v[228:229], 0 op_sel_hi:[1,0]
	s_nop 0
	v_pk_add_f32 v[228:229], v[228:229], v[232:233]
	v_pk_add_f32 v[228:229], v[228:229], v[236:237]
	v_pk_add_f32 v[228:229], v[228:229], v[240:241]
	v_pk_fma_f32 v[154:155], v[228:229], v[244:245], v[154:155]
	v_add_u32_e32 v47, 0x800, v112
	v_add_u32_e32 v45, 0x800, v114
	v_add_u32_e32 v157, 0x800, v113
	v_lshrrev_b32_e32 v158, 16, v47
	v_add_u32_e32 v156, 0x800, v115
	v_lshlrev_b32_e32 v47, 4, v47
	v_and_b32_e32 v47, 0xf0000, v47
	v_add_u32_e32 v36, 0x800, v110
	v_add_u32_e32 v37, 0x800, v108
	v_add_u32_e32 v38, 0x800, v111
	v_add_u32_e32 v39, 0x800, v109
	v_lshrrev_b32_e32 v32, 16, v36
	v_lshrrev_b32_e32 v34, 16, v37
	v_and_or_b32 v33, v38, s4, v32
	v_and_or_b32 v32, v39, s4, v34
	v_lshrrev_b32_e32 v37, 12, v37
	v_lshrrev_b32_e32 v39, 8, v39
	v_lshrrev_b32_e32 v36, 4, v36
	v_and_b32_e32 v38, 0xf000, v38
	v_lshrrev_b32_e32 v35, 16, v45
	v_and_or_b32 v34, v157, s4, v158
	v_and_b32_e32 v39, 0xf0, v39
	v_and_b32_e32 v36, 0xf00, v36
	v_lshlrev_b32_e32 v157, 8, v157
	v_and_or_b32 v37, v37, 15, v38
	v_and_or_b32 v35, v156, s4, v35
	v_and_b32_e32 v157, 0xf00000, v157
	v_lshlrev_b32_e32 v45, 12, v45
	v_lshlrev_b32_e32 v156, 16, v156
	v_or3_b32 v36, v37, v39, v36
	v_and_b32_e32 v45, 0xf000000, v45
	v_and_b32_e32 v156, 0xf0000000, v156
	v_or3_b32 v36, v36, v47, v157
	v_or3_b32 v36, v36, v45, v156
	global_store_dwordx4 v[124:125], v[32:35], off nt
	global_store_dword v[126:127], v36, off nt
	v_add_u32_e32 v36, 0x800, v118
	v_add_u32_e32 v37, 0x800, v116
	v_add_u32_e32 v38, 0x800, v119
	v_add_u32_e32 v39, 0x800, v117
	v_add_u32_e32 v47, 0x800, v120
	v_lshrrev_b32_e32 v32, 16, v36
	v_lshrrev_b32_e32 v34, 16, v37
	v_add_u32_e32 v45, 0x800, v122
	v_add_u32_e32 v125, 0x800, v121
	v_lshrrev_b32_e32 v126, 16, v47
	v_and_or_b32 v33, v38, s4, v32
	v_and_or_b32 v32, v39, s4, v34
	v_lshrrev_b32_e32 v37, 12, v37
	v_lshrrev_b32_e32 v39, 8, v39
	v_lshrrev_b32_e32 v36, 4, v36
	v_and_b32_e32 v38, 0xf000, v38
	v_add_u32_e32 v124, 0x800, v123
	v_lshrrev_b32_e32 v35, 16, v45
	v_and_or_b32 v34, v125, s4, v126
	v_and_b32_e32 v39, 0xf0, v39
	v_and_b32_e32 v36, 0xf00, v36
	v_lshlrev_b32_e32 v47, 4, v47
	v_lshlrev_b32_e32 v125, 8, v125
	v_and_or_b32 v37, v37, 15, v38
	v_and_or_b32 v35, v124, s4, v35
	v_and_b32_e32 v47, 0xf0000, v47
	v_and_b32_e32 v125, 0xf00000, v125
	v_lshlrev_b32_e32 v45, 12, v45
	v_lshlrev_b32_e32 v124, 16, v124
	v_or3_b32 v36, v37, v39, v36
	v_and_b32_e32 v45, 0xf000000, v45
	v_and_b32_e32 v124, 0xf0000000, v124
	v_or3_b32 v36, v36, v47, v125
	v_or3_b32 v36, v36, v45, v124
	global_store_dwordx4 v[136:137], v[32:35], off nt
	global_store_dword v[138:139], v36, off nt
	v_add_u32_e32 v36, 0x800, v130
	v_add_u32_e32 v37, 0x800, v128
	v_add_u32_e32 v38, 0x800, v131
	v_add_u32_e32 v39, 0x800, v129
	v_add_u32_e32 v47, 0x800, v132
	v_lshrrev_b32_e32 v32, 16, v36
	v_lshrrev_b32_e32 v34, 16, v37
	v_add_u32_e32 v45, 0x800, v134
	v_add_u32_e32 v125, 0x800, v133
	v_lshrrev_b32_e32 v126, 16, v47
	v_and_or_b32 v33, v38, s4, v32
	v_and_or_b32 v32, v39, s4, v34
	v_lshrrev_b32_e32 v37, 12, v37
	v_lshrrev_b32_e32 v39, 8, v39
	v_lshrrev_b32_e32 v36, 4, v36
	v_and_b32_e32 v38, 0xf000, v38
	v_add_u32_e32 v124, 0x800, v135
	v_lshrrev_b32_e32 v35, 16, v45
	v_and_or_b32 v34, v125, s4, v126
	v_and_b32_e32 v39, 0xf0, v39
	v_and_b32_e32 v36, 0xf00, v36
	v_lshlrev_b32_e32 v47, 4, v47
	v_lshlrev_b32_e32 v125, 8, v125
	v_and_or_b32 v37, v37, 15, v38
	v_and_or_b32 v35, v124, s4, v35
	v_and_b32_e32 v47, 0xf0000, v47
	v_and_b32_e32 v125, 0xf00000, v125
	v_lshlrev_b32_e32 v45, 12, v45
	v_lshlrev_b32_e32 v124, 16, v124
	v_or3_b32 v36, v37, v39, v36
	v_and_b32_e32 v45, 0xf000000, v45
	v_and_b32_e32 v124, 0xf0000000, v124
	v_or3_b32 v36, v36, v47, v125
	v_or3_b32 v36, v36, v45, v124
	global_store_dwordx4 v[140:141], v[32:35], off nt
	global_store_dword v[142:143], v36, off nt
	v_add_u32_e32 v36, 0x800, v150
	v_add_u32_e32 v37, 0x800, v148
	v_add_u32_e32 v38, 0x800, v151
	v_add_u32_e32 v39, 0x800, v149
	v_add_u32_e32 v47, 0x800, v152
	v_lshrrev_b32_e32 v32, 16, v36
	v_lshrrev_b32_e32 v34, 16, v37
	v_add_u32_e32 v45, 0x800, v154
	v_add_u32_e32 v125, 0x800, v153
	v_lshrrev_b32_e32 v126, 16, v47
	v_and_or_b32 v33, v38, s4, v32
	v_and_or_b32 v32, v39, s4, v34
	v_lshrrev_b32_e32 v37, 12, v37
	v_lshrrev_b32_e32 v39, 8, v39
	v_lshrrev_b32_e32 v36, 4, v36
	v_and_b32_e32 v38, 0xf000, v38
	v_add_u32_e32 v124, 0x800, v155
	v_lshrrev_b32_e32 v35, 16, v45
	v_and_or_b32 v34, v125, s4, v126
	v_and_b32_e32 v39, 0xf0, v39
	v_and_b32_e32 v36, 0xf00, v36
	v_lshlrev_b32_e32 v47, 4, v47
	v_lshlrev_b32_e32 v125, 8, v125
	v_and_or_b32 v37, v37, 15, v38
	v_and_or_b32 v35, v124, s4, v35
	v_and_b32_e32 v47, 0xf0000, v47
	v_and_b32_e32 v125, 0xf00000, v125
	v_lshlrev_b32_e32 v45, 12, v45
	v_lshlrev_b32_e32 v124, 16, v124
	v_or3_b32 v36, v37, v39, v36
	v_and_b32_e32 v45, 0xf000000, v45
	v_and_b32_e32 v124, 0xf0000000, v124
	v_or3_b32 v36, v36, v47, v125
	v_or3_b32 v36, v36, v45, v124
	global_store_dwordx4 v[144:145], v[32:35], off nt
	global_store_dword v[146:147], v36, off nt
	s_branch .LBB0_1129

; #define GAS __attribute__((address_space(1)))
; __device__ __forceinline__ void norm_phase(bool from_input, int gw, int NGW, int lane_in, float* H, const float* x_in, const float* c_in, const float* gain, const float* modL, int js, int jc, bf16* XN, ...
;     ...
;         if (pend) {
; #pragma unroll
;             for (int j = 0; j < 4; ++j) { const int c0 = 8 * (lane + 64 * j); f32x4 a0 = {0.f, 0.f, 0.f, 0.f}, a1 = a0;
;                 for (int qs = 0; qs < nsl; ++qs) { const GAS f32x4* sp = (const GAS f32x4*)(SLAB + ((size_t)qs * 512 + b * 256 + s) * 2048 + c0); a0 += sp[0]; a1 += sp[1]; }
;                 const f32x4 g0 = *(const f32x4*)(sgate + c0) * scoef, g1 = *(const f32x4*)(sgate + c0 + 4) * scoef;
; #pragma unroll
;                 for (int q = 0; q < 4; ++q) { v[j][q] += g0[q] * a0[q]; v[j][4 + q] += g1[q] * a1[q]; } }
.LBB0_1488:
	s_andn2_b64 vcc, exec, s[0:1]
	s_cbranch_vccnz .LBB0_1479
	s_lshl_b32 s0, s3, 8
	s_or_b32 s0, s0, s10
	s_mov_b32 s1, s21
	s_lshl_b64 s[0:1], s[0:1], 13
	s_waitcnt vmcnt(0)
	v_lshl_add_u64 v[206:207], v[58:59], 0, s[0:1]
	v_lshl_add_u64 v[210:211], v[58:59], 0, s[0:1]
	v_lshl_add_u64 v[210:211], v[210:211], 0, s[40:41]
	v_lshl_add_u64 v[214:215], v[58:59], 0, s[0:1]
	v_lshl_add_u64 v[214:215], v[214:215], 0, s[48:49]
	v_lshl_add_u64 v[218:219], v[58:59], 0, s[0:1]
	v_lshl_add_u64 v[218:219], v[218:219], 0, s[54:55]
	v_lshl_add_u64 v[226:227], v[58:59], 0, s[0:1]
	v_lshl_add_u64 v[230:231], v[58:59], 0, s[0:1]
	v_add_co_u32_e32 v230, vcc, s6, v230
	s_nop 1
	v_addc_co_u32_e32 v231, vcc, 0, v231, vcc
	v_lshl_add_u64 v[234:235], v[58:59], 0, s[0:1]
	v_add_co_u32_e32 v234, vcc, s7, v234
	s_nop 1
	v_addc_co_u32_e32 v235, vcc, 0, v235, vcc
	v_lshl_add_u64 v[238:239], v[58:59], 0, s[0:1]
	v_add_co_u32_e32 v238, vcc, s8, v238
	s_nop 1
	v_addc_co_u32_e32 v239, vcc, 0, v239, vcc
	global_load_dwordx4 v[206:209], v[206:207], off offset:16
	global_load_dwordx4 v[210:213], v[210:211], off offset:16
	global_load_dwordx4 v[214:217], v[214:215], off offset:16
	global_load_dwordx4 v[218:221], v[218:219], off offset:16
	global_load_dwordx4 v[222:225], v[60:61], off offset:16
	global_load_dwordx4 v[226:229], v[226:227], off
	global_load_dwordx4 v[230:233], v[230:231], off
	global_load_dwordx4 v[234:237], v[234:235], off
	global_load_dwordx4 v[238:241], v[238:239], off
	global_load_dwordx4 v[242:245], v[60:61], off
	s_waitcnt vmcnt(0)
	v_pk_add_f32 v[206:207], v[206:207], 0 op_sel_hi:[1,0]
	s_nop 0
	v_pk_add_f32 v[206:207], v[206:207], v[210:211]
	v_pk_add_f32 v[206:207], v[206:207], v[214:215]
	v_pk_add_f32 v[206:207], v[206:207], v[218:219]
	v_pk_mul_f32 v[222:223], v[222:223], 0.5 op_sel_hi:[1,0]
	s_nop 0
	v_pk_fma_f32 v[112:113], v[206:207], v[222:223], v[112:113]
	v_pk_add_f32 v[226:227], v[226:227], 0 op_sel_hi:[1,0]
	s_nop 0
	v_pk_add_f32 v[226:227], v[226:227], v[230:231]
	v_pk_add_f32 v[226:227], v[226:227], v[234:235]
	v_pk_add_f32 v[226:227], v[226:227], v[238:239]
	v_pk_mul_f32 v[242:243], v[242:243], 0.5 op_sel_hi:[1,0]
	s_nop 0
	v_pk_fma_f32 v[108:109], v[226:227], v[242:243], v[108:109]
	v_pk_add_f32 v[228:229], v[228:229], 0 op_sel_hi:[1,0]
	s_nop 0
	v_pk_add_f32 v[228:229], v[228:229], v[232:233]
	v_pk_add_f32 v[228:229], v[228:229], v[236:237]
	v_pk_add_f32 v[228:229], v[228:229], v[240:241]
	v_pk_mul_f32 v[244:245], v[244:245], 0.5 op_sel_hi:[1,0]
	s_nop 0
	v_pk_fma_f32 v[110:111], v[228:229], v[244:245], v[110:111]
	v_pk_add_f32 v[208:209], v[208:209], 0 op_sel_hi:[1,0]
	s_nop 0
	v_pk_add_f32 v[208:209], v[208:209], v[212:213]
	v_pk_add_f32 v[208:209], v[208:209], v[216:217]
	v_pk_add_f32 v[208:209], v[208:209], v[220:221]
	v_pk_mul_f32 v[224:225], v[224:225], 0.5 op_sel_hi:[1,0]
	s_nop 0
	v_pk_fma_f32 v[114:115], v[208:209], v[224:225], v[114:115]
	v_lshl_add_u64 v[206:207], v[72:73], 0, s[0:1]
	v_lshl_add_u64 v[210:211], v[72:73], 0, s[0:1]
	v_lshl_add_u64 v[210:211], v[210:211], 0, s[40:41]
	v_lshl_add_u64 v[214:215], v[72:73], 0, s[0:1]
	v_lshl_add_u64 v[214:215], v[214:215], 0, s[48:49]
	v_lshl_add_u64 v[218:219], v[72:73], 0, s[0:1]
	v_lshl_add_u64 v[218:219], v[218:219], 0, s[54:55]
	v_lshl_add_u64 v[226:227], v[72:73], 0, s[0:1]
	v_lshl_add_u64 v[230:231], v[72:73], 0, s[0:1]
	v_add_co_u32_e32 v230, vcc, s6, v230
	s_nop 1
	v_addc_co_u32_e32 v231, vcc, 0, v231, vcc
	v_lshl_add_u64 v[234:235], v[72:73], 0, s[0:1]
	v_add_co_u32_e32 v234, vcc, s7, v234
	s_nop 1
	v_addc_co_u32_e32 v235, vcc, 0, v235, vcc
	v_lshl_add_u64 v[238:239], v[72:73], 0, s[0:1]
	v_add_co_u32_e32 v238, vcc, s8, v238
	s_nop 1
	v_addc_co_u32_e32 v239, vcc, 0, v239, vcc
	global_load_dwordx4 v[206:209], v[206:207], off offset:16
	global_load_dwordx4 v[210:213], v[210:211], off offset:16
	global_load_dwordx4 v[214:217], v[214:215], off offset:16
	global_load_dwordx4 v[218:221], v[218:219], off offset:16
	global_load_dwordx4 v[222:225], v[62:63], off offset:16
	global_load_dwordx4 v[226:229], v[226:227], off
	global_load_dwordx4 v[230:233], v[230:231], off
	global_load_dwordx4 v[234:237], v[234:235], off
	global_load_dwordx4 v[238:241], v[238:239], off
	global_load_dwordx4 v[242:245], v[62:63], off
	s_waitcnt vmcnt(0)
; #define GAS __attribute__((address_space(1)))
; __device__ __forceinline__ void norm_phase(bool from_input, int gw, int NGW, int lane_in, float* H, const float* x_in, const float* c_in, const float* gain, const float* modL, int js, int jc, bf16* XN, ...
;     ...
;             for (int j = 0; j < 4; ++j) { const int c0 = 8 * (lane + 64 * j); f32x4 a0 = {0.f, 0.f, 0.f, 0.f}, a1 = a0;
;                 for (int qs = 0; qs < nsl; ++qs) { const GAS f32x4* sp = (const GAS f32x4*)(SLAB + ((size_t)qs * 512 + b * 256 + s) * 2048 + c0); a0 += sp[0]; a1 += sp[1]; }
;                 const f32x4 g0 = *(const f32x4*)(sgate + c0) * scoef, g1 = *(const f32x4*)(sgate + c0 + 4) * scoef;
; #pragma unroll
;                 for (int q = 0; q < 4; ++q) { v[j][q] += g0[q] * a0[q]; v[j][4 + q] += g1[q] * a1[q]; } }
	v_pk_add_f32 v[206:207], v[206:207], 0 op_sel_hi:[1,0]
	s_nop 0
	v_pk_add_f32 v[206:207], v[206:207], v[210:211]
	v_pk_add_f32 v[206:207], v[206:207], v[214:215]
	v_pk_add_f32 v[206:207], v[206:207], v[218:219]
	v_pk_mul_f32 v[222:223], v[222:223], 0.5 op_sel_hi:[1,0]
	s_nop 0
	v_pk_fma_f32 v[120:121], v[206:207], v[222:223], v[120:121]
	v_pk_add_f32 v[226:227], v[226:227], 0 op_sel_hi:[1,0]
	s_nop 0
	v_pk_add_f32 v[226:227], v[226:227], v[230:231]
	v_pk_add_f32 v[226:227], v[226:227], v[234:235]
	v_pk_add_f32 v[226:227], v[226:227], v[238:239]
	v_pk_mul_f32 v[242:243], v[242:243], 0.5 op_sel_hi:[1,0]
	s_nop 0
	v_pk_fma_f32 v[116:117], v[226:227], v[242:243], v[116:117]
	v_pk_add_f32 v[228:229], v[228:229], 0 op_sel_hi:[1,0]
	s_nop 0
	v_pk_add_f32 v[228:229], v[228:229], v[232:233]
	v_pk_add_f32 v[228:229], v[228:229], v[236:237]
	v_pk_add_f32 v[228:229], v[228:229], v[240:241]
	v_pk_mul_f32 v[244:245], v[244:245], 0.5 op_sel_hi:[1,0]
	s_nop 0
	v_pk_fma_f32 v[118:119], v[228:229], v[244:245], v[118:119]
	v_pk_add_f32 v[208:209], v[208:209], 0 op_sel_hi:[1,0]
	s_nop 0
	v_pk_add_f32 v[208:209], v[208:209], v[212:213]
	v_pk_add_f32 v[208:209], v[208:209], v[216:217]
	v_pk_add_f32 v[208:209], v[208:209], v[220:221]
	v_pk_mul_f32 v[224:225], v[224:225], 0.5 op_sel_hi:[1,0]
	s_nop 0
	v_pk_fma_f32 v[122:123], v[208:209], v[224:225], v[122:123]
	v_lshl_add_u64 v[206:207], v[64:65], 0, s[0:1]
	v_lshl_add_u64 v[210:211], v[64:65], 0, s[0:1]
	v_add_co_u32_e32 v210, vcc, s6, v210
	s_nop 1
	v_addc_co_u32_e32 v211, vcc, 0, v211, vcc
	v_lshl_add_u64 v[214:215], v[64:65], 0, s[0:1]
	v_add_co_u32_e32 v214, vcc, s7, v214
	s_nop 1
	v_addc_co_u32_e32 v215, vcc, 0, v215, vcc
	v_lshl_add_u64 v[218:219], v[64:65], 0, s[0:1]
	v_add_co_u32_e32 v218, vcc, s8, v218
	s_nop 1
	v_addc_co_u32_e32 v219, vcc, 0, v219, vcc
	v_lshl_add_u64 v[226:227], v[64:65], 0, s[0:1]
	v_lshl_add_u64 v[230:231], v[64:65], 0, s[0:1]
	v_lshl_add_u64 v[230:231], v[230:231], 0, s[40:41]
	v_lshl_add_u64 v[234:235], v[64:65], 0, s[0:1]
	v_lshl_add_u64 v[234:235], v[234:235], 0, s[48:49]
	v_lshl_add_u64 v[238:239], v[64:65], 0, s[0:1]
	v_lshl_add_u64 v[238:239], v[238:239], 0, s[54:55]
	global_load_dwordx4 v[206:209], v[206:207], off
	global_load_dwordx4 v[210:213], v[210:211], off
	global_load_dwordx4 v[214:217], v[214:215], off
	global_load_dwordx4 v[218:221], v[218:219], off
	global_load_dwordx4 v[222:225], v[66:67], off
	global_load_dwordx4 v[226:229], v[226:227], off offset:16
	global_load_dwordx4 v[230:233], v[230:231], off offset:16
	global_load_dwordx4 v[234:237], v[234:235], off offset:16
	global_load_dwordx4 v[238:241], v[238:239], off offset:16
	global_load_dwordx4 v[242:245], v[66:67], off offset:16
	s_waitcnt vmcnt(0)
	v_pk_add_f32 v[206:207], v[206:207], 0 op_sel_hi:[1,0]
	s_nop 0
	v_pk_add_f32 v[206:207], v[206:207], v[210:211]
	v_pk_add_f32 v[206:207], v[206:207], v[214:215]
	v_pk_add_f32 v[206:207], v[206:207], v[218:219]
	v_pk_mul_f32 v[222:223], v[222:223], 0.5 op_sel_hi:[1,0]
	s_nop 0
	v_pk_fma_f32 v[128:129], v[206:207], v[222:223], v[128:129]
	v_pk_add_f32 v[226:227], v[226:227], 0 op_sel_hi:[1,0]
	s_nop 0
	v_pk_add_f32 v[226:227], v[226:227], v[230:231]
	v_pk_add_f32 v[226:227], v[226:227], v[234:235]
	v_pk_add_f32 v[226:227], v[226:227], v[238:239]
	v_pk_mul_f32 v[242:243], v[242:243], 0.5 op_sel_hi:[1,0]
	s_nop 0
	v_pk_fma_f32 v[132:133], v[226:227], v[242:243], v[132:133]
	v_pk_add_f32 v[208:209], v[208:209], 0 op_sel_hi:[1,0]
	s_nop 0
	v_pk_add_f32 v[208:209], v[208:209], v[212:213]
	v_pk_add_f32 v[208:209], v[208:209], v[216:217]
	v_pk_add_f32 v[208:209], v[208:209], v[220:221]
	v_pk_mul_f32 v[224:225], v[224:225], 0.5 op_sel_hi:[1,0]
	s_nop 0
	v_pk_fma_f32 v[130:131], v[208:209], v[224:225], v[130:131]
	v_pk_add_f32 v[228:229], v[228:229], 0 op_sel_hi:[1,0]
	s_nop 0
	v_pk_add_f32 v[228:229], v[228:229], v[232:233]
	v_pk_add_f32 v[228:229], v[228:229], v[236:237]
	v_pk_add_f32 v[228:229], v[228:229], v[240:241]
	v_pk_mul_f32 v[244:245], v[244:245], 0.5 op_sel_hi:[1,0]
	s_nop 0
	v_pk_fma_f32 v[134:135], v[228:229], v[244:245], v[134:135]
	v_lshl_add_u64 v[206:207], v[68:69], 0, s[0:1]
	v_lshl_add_u64 v[210:211], v[68:69], 0, s[0:1]
	v_lshl_add_u64 v[210:211], v[210:211], 0, s[40:41]
	v_lshl_add_u64 v[214:215], v[68:69], 0, s[0:1]
	v_lshl_add_u64 v[214:215], v[214:215], 0, s[48:49]
	v_lshl_add_u64 v[218:219], v[68:69], 0, s[0:1]
	v_lshl_add_u64 v[218:219], v[218:219], 0, s[54:55]
	v_lshl_add_u64 v[226:227], v[68:69], 0, s[0:1]
	v_lshl_add_u64 v[230:231], v[68:69], 0, s[0:1]
	v_add_co_u32_e32 v230, vcc, s6, v230
	s_nop 1
	v_addc_co_u32_e32 v231, vcc, 0, v231, vcc
	v_lshl_add_u64 v[234:235], v[68:69], 0, s[0:1]
	v_add_co_u32_e32 v234, vcc, s7, v234
	s_nop 1
	v_addc_co_u32_e32 v235, vcc, 0, v235, vcc
	v_lshl_add_u64 v[238:239], v[68:69], 0, s[0:1]
	v_add_co_u32_e32 v238, vcc, s8, v238
	s_nop 1
	v_addc_co_u32_e32 v239, vcc, 0, v239, vcc
	global_load_dwordx4 v[206:209], v[206:207], off offset:16
	global_load_dwordx4 v[210:213], v[210:211], off offset:16
	global_load_dwordx4 v[214:217], v[214:215], off offset:16
	global_load_dwordx4 v[218:221], v[218:219], off offset:16
	global_load_dwordx4 v[222:225], v[70:71], off offset:16
	global_load_dwordx4 v[226:229], v[226:227], off
	global_load_dwordx4 v[230:233], v[230:231], off
	global_load_dwordx4 v[234:237], v[234:235], off
	global_load_dwordx4 v[238:241], v[238:239], off
	global_load_dwordx4 v[242:245], v[70:71], off
	s_waitcnt vmcnt(0)
; #define GAS __attribute__((address_space(1)))
; __device__ __forceinline__ void h24_store(unsigned char* Hb, size_t r, int lane, const float (&v)[4][8]) {
; #pragma unroll
;     for (int j = 0; j < 4; ++j) { const size_t e = r * 2048 + 8 * (lane + 64 * j); unsigned u[8];
; #pragma unroll
;         for (int q = 0; q < 8; ++q) u[q] = __builtin_bit_cast(unsigned, v[j][q]) + 0x800u;
;         v4u hi; unsigned lo = 0u;
; #pragma unroll
;         for (int q = 0; q < 4; ++q) hi[q] = (u[2 * q] >> 16) | (u[2 * q + 1] & 0xffff0000u);
; #pragma unroll
;         for (int q = 0; q < 8; ++q) lo |= ((u[q] >> 12) & 0xfu) << (4 * q);
;         __builtin_nontemporal_store(hi, (GAS v4u*)(Hb + e * 2)); __builtin_nontemporal_store(lo, (GAS unsigned*)(Hb + H_LO_OFF + (e >> 1))); }
; __device__ __forceinline__ void norm_phase(bool from_input, int gw, int NGW, int lane_in, float* H, const float* x_in, const float* c_in, const float* gain, const float* modL, int js, int jc, bf16* XN, ...
;     ...
;             for (int j = 0; j < 4; ++j) { const int c0 = 8 * (lane + 64 * j); f32x4 a0 = {0.f, 0.f, 0.f, 0.f}, a1 = a0;
;                 for (int qs = 0; qs < nsl; ++qs) { const GAS f32x4* sp = (const GAS f32x4*)(SLAB + ((size_t)qs * 512 + b * 256 + s) * 2048 + c0); a0 += sp[0]; a1 += sp[1]; }
;                 const f32x4 g0 = *(const f32x4*)(sgate + c0) * scoef, g1 = *(const f32x4*)(sgate + c0 + 4) * scoef;
; #pragma unroll
;                 for (int q = 0; q < 4; ++q) { v[j][q] += g0[q] * a0[q]; v[j][4 + q] += g1[q] * a1[q]; } }
;             h24_store(Hb, (size_t)r, lane, v);
	v_pk_add_f32 v[206:207], v[206:207], 0 op_sel_hi:[1,0]
	s_nop 0
	v_pk_add_f32 v[206:207], v[206:207], v[210:211]
	v_pk_add_f32 v[206:207], v[206:207], v[214:215]
	v_pk_add_f32 v[206:207], v[206:207], v[218:219]
	v_pk_mul_f32 v[222:223], v[222:223], 0.5 op_sel_hi:[1,0]
	s_nop 0
	v_pk_fma_f32 v[152:153], v[206:207], v[222:223], v[152:153]
	v_pk_add_f32 v[226:227], v[226:227], 0 op_sel_hi:[1,0]
	s_nop 0
	v_pk_add_f32 v[226:227], v[226:227], v[230:231]
	v_pk_add_f32 v[226:227], v[226:227], v[234:235]
	v_pk_add_f32 v[226:227], v[226:227], v[238:239]
	v_pk_mul_f32 v[242:243], v[242:243], 0.5 op_sel_hi:[1,0]
	s_nop 0
	v_pk_fma_f32 v[148:149], v[226:227], v[242:243], v[148:149]
	v_pk_add_f32 v[228:229], v[228:229], 0 op_sel_hi:[1,0]
	s_nop 0
	v_pk_add_f32 v[228:229], v[228:229], v[232:233]
	v_pk_add_f32 v[228:229], v[228:229], v[236:237]
	v_pk_add_f32 v[228:229], v[228:229], v[240:241]
	v_pk_mul_f32 v[244:245], v[244:245], 0.5 op_sel_hi:[1,0]
	s_nop 0
	v_pk_fma_f32 v[150:151], v[228:229], v[244:245], v[150:151]
	v_pk_add_f32 v[208:209], v[208:209], 0 op_sel_hi:[1,0]
	s_nop 0
	v_pk_add_f32 v[208:209], v[208:209], v[212:213]
	v_pk_add_f32 v[208:209], v[208:209], v[216:217]
	v_pk_add_f32 v[208:209], v[208:209], v[220:221]
	v_pk_mul_f32 v[224:225], v[224:225], 0.5 op_sel_hi:[1,0]
	s_nop 0
	v_pk_fma_f32 v[154:155], v[208:209], v[224:225], v[154:155]
	v_add_u32_e32 v47, 0x800, v112
	v_add_u32_e32 v45, 0x800, v114
	v_add_u32_e32 v36, 0x800, v110
	v_add_u32_e32 v37, 0x800, v108
	v_add_u32_e32 v38, 0x800, v111
	v_add_u32_e32 v39, 0x800, v109
	v_lshrrev_b32_e32 v32, 16, v36
	v_lshrrev_b32_e32 v34, 16, v37
	v_add_u32_e32 v157, 0x800, v113
	v_lshrrev_b32_e32 v158, 16, v47
	v_and_or_b32 v33, v38, s4, v32
	v_and_or_b32 v32, v39, s4, v34
	v_lshrrev_b32_e32 v37, 12, v37
	v_lshrrev_b32_e32 v39, 8, v39
	v_lshrrev_b32_e32 v36, 4, v36
	v_and_b32_e32 v38, 0xf000, v38
	v_add_u32_e32 v156, 0x800, v115
	v_lshrrev_b32_e32 v35, 16, v45
	v_and_or_b32 v34, v157, s4, v158
	v_and_b32_e32 v39, 0xf0, v39
	v_and_b32_e32 v36, 0xf00, v36
	v_lshlrev_b32_e32 v47, 4, v47
	v_lshlrev_b32_e32 v157, 8, v157
	v_and_or_b32 v37, v37, 15, v38
	v_and_or_b32 v35, v156, s4, v35
	v_and_b32_e32 v47, 0xf0000, v47
	v_and_b32_e32 v157, 0xf00000, v157
	v_lshlrev_b32_e32 v45, 12, v45
	v_lshlrev_b32_e32 v156, 16, v156
	v_or3_b32 v36, v37, v39, v36
	v_and_b32_e32 v45, 0xf000000, v45
	v_and_b32_e32 v156, 0xf0000000, v156
	v_or3_b32 v36, v36, v47, v157
	v_or3_b32 v36, v36, v45, v156
	global_store_dwordx4 v[124:125], v[32:35], off nt
	global_store_dword v[126:127], v36, off nt
	v_add_u32_e32 v36, 0x800, v118
	v_add_u32_e32 v37, 0x800, v116
	v_add_u32_e32 v38, 0x800, v119
	v_add_u32_e32 v39, 0x800, v117
	v_add_u32_e32 v47, 0x800, v120
	v_lshrrev_b32_e32 v32, 16, v36
	v_lshrrev_b32_e32 v34, 16, v37
	v_add_u32_e32 v45, 0x800, v122
	v_add_u32_e32 v125, 0x800, v121
	v_lshrrev_b32_e32 v126, 16, v47
	v_and_or_b32 v33, v38, s4, v32
	v_and_or_b32 v32, v39, s4, v34
	v_lshrrev_b32_e32 v37, 12, v37
	v_lshrrev_b32_e32 v39, 8, v39
	v_lshrrev_b32_e32 v36, 4, v36
	v_and_b32_e32 v38, 0xf000, v38
	v_add_u32_e32 v124, 0x800, v123
	v_lshrrev_b32_e32 v35, 16, v45
	v_and_or_b32 v34, v125, s4, v126
	v_and_b32_e32 v39, 0xf0, v39
	v_and_b32_e32 v36, 0xf00, v36
	v_lshlrev_b32_e32 v47, 4, v47
	v_lshlrev_b32_e32 v125, 8, v125
	v_and_or_b32 v37, v37, 15, v38
	v_and_or_b32 v35, v124, s4, v35
	v_and_b32_e32 v47, 0xf0000, v47
	v_and_b32_e32 v125, 0xf00000, v125
	v_lshlrev_b32_e32 v45, 12, v45
	v_lshlrev_b32_e32 v124, 16, v124
	v_or3_b32 v36, v37, v39, v36
	v_and_b32_e32 v45, 0xf000000, v45
	v_and_b32_e32 v124, 0xf0000000, v124
	v_or3_b32 v36, v36, v47, v125
	v_or3_b32 v36, v36, v45, v124
	global_store_dwordx4 v[136:137], v[32:35], off nt
	global_store_dword v[138:139], v36, off nt
	v_add_u32_e32 v36, 0x800, v130
	v_add_u32_e32 v37, 0x800, v128
	v_add_u32_e32 v38, 0x800, v131
	v_add_u32_e32 v39, 0x800, v129
	v_add_u32_e32 v47, 0x800, v132
	v_lshrrev_b32_e32 v32, 16, v36
	v_lshrrev_b32_e32 v34, 16, v37
	v_add_u32_e32 v45, 0x800, v134
	v_add_u32_e32 v125, 0x800, v133
	v_lshrrev_b32_e32 v126, 16, v47
	v_and_or_b32 v33, v38, s4, v32
	v_and_or_b32 v32, v39, s4, v34
	v_lshrrev_b32_e32 v37, 12, v37
	v_lshrrev_b32_e32 v39, 8, v39
	v_lshrrev_b32_e32 v36, 4, v36
	v_and_b32_e32 v38, 0xf000, v38
	v_add_u32_e32 v124, 0x800, v135
	v_lshrrev_b32_e32 v35, 16, v45
	v_and_or_b32 v34, v125, s4, v126
	v_and_b32_e32 v39, 0xf0, v39
	v_and_b32_e32 v36, 0xf00, v36
	v_lshlrev_b32_e32 v47, 4, v47
	v_lshlrev_b32_e32 v125, 8, v125
	v_and_or_b32 v37, v37, 15, v38
	v_and_or_b32 v35, v124, s4, v35
	v_and_b32_e32 v47, 0xf0000, v47
	v_and_b32_e32 v125, 0xf00000, v125
	v_lshlrev_b32_e32 v45, 12, v45
	v_lshlrev_b32_e32 v124, 16, v124
	v_or3_b32 v36, v37, v39, v36
	v_and_b32_e32 v45, 0xf000000, v45
	v_and_b32_e32 v124, 0xf0000000, v124
	v_or3_b32 v36, v36, v47, v125
	v_or3_b32 v36, v36, v45, v124
	global_store_dwordx4 v[140:141], v[32:35], off nt
	global_store_dword v[142:143], v36, off nt
	v_add_u32_e32 v36, 0x800, v150
	v_add_u32_e32 v37, 0x800, v148
	v_add_u32_e32 v38, 0x800, v151
	v_add_u32_e32 v39, 0x800, v149
	v_add_u32_e32 v47, 0x800, v152
	v_lshrrev_b32_e32 v32, 16, v36
	v_lshrrev_b32_e32 v34, 16, v37
	v_add_u32_e32 v45, 0x800, v154
	v_add_u32_e32 v125, 0x800, v153
	v_lshrrev_b32_e32 v126, 16, v47
	v_and_or_b32 v33, v38, s4, v32
	v_and_or_b32 v32, v39, s4, v34
	v_lshrrev_b32_e32 v37, 12, v37
	v_lshrrev_b32_e32 v39, 8, v39
	v_lshrrev_b32_e32 v36, 4, v36
	v_and_b32_e32 v38, 0xf000, v38
	v_add_u32_e32 v124, 0x800, v155
	v_lshrrev_b32_e32 v35, 16, v45
	v_and_or_b32 v34, v125, s4, v126
	v_and_b32_e32 v39, 0xf0, v39
	v_and_b32_e32 v36, 0xf00, v36
	v_lshlrev_b32_e32 v47, 4, v47
	v_lshlrev_b32_e32 v125, 8, v125
	v_and_or_b32 v37, v37, 15, v38
	v_and_or_b32 v35, v124, s4, v35
	v_and_b32_e32 v47, 0xf0000, v47
	v_and_b32_e32 v125, 0xf00000, v125
	v_lshlrev_b32_e32 v45, 12, v45
	v_lshlrev_b32_e32 v124, 16, v124
	v_or3_b32 v36, v37, v39, v36
	v_and_b32_e32 v45, 0xf000000, v45
	v_and_b32_e32 v124, 0xf0000000, v124
	v_or3_b32 v36, v36, v47, v125
	v_or3_b32 v36, v36, v45, v124
	global_store_dwordx4 v[144:145], v[32:35], off nt
	global_store_dword v[146:147], v36, off nt
	s_branch .LBB0_1479

; #define GAS __attribute__((address_space(1)))
; __device__ __forceinline__ void norm_phase(bool from_input, int gw, int NGW, int lane_in, float* H, const float* x_in, const float* c_in, const float* gain, const float* modL, int js, int jc, bf16* XN, ...
;     ...
;         if (pend) {
; #pragma unroll
;             for (int j = 0; j < 4; ++j) { const int c0 = 8 * (lane + 64 * j); f32x4 a0 = {0.f, 0.f, 0.f, 0.f}, a1 = a0;
;                 for (int qs = 0; qs < nsl; ++qs) { const GAS f32x4* sp = (const GAS f32x4*)(SLAB + ((size_t)qs * 512 + b * 256 + s) * 2048 + c0); a0 += sp[0]; a1 += sp[1]; }
;                 const f32x4 g0 = *(const f32x4*)(sgate + c0) * scoef, g1 = *(const f32x4*)(sgate + c0 + 4) * scoef;
; #pragma unroll
;                 for (int q = 0; q < 4; ++q) { v[j][q] += g0[q] * a0[q]; v[j][4 + q] += g1[q] * a1[q]; } }
.LBB0_1838:
	s_andn2_b64 vcc, exec, s[0:1]
	s_cbranch_vccnz .LBB0_1829
	s_lshl_b32 s0, s3, 8
	s_or_b32 s0, s0, s10
	s_mov_b32 s1, s21
	s_lshl_b64 s[0:1], s[0:1], 13
	s_waitcnt vmcnt(0)
	v_lshl_add_u64 v[206:207], v[58:59], 0, s[0:1]
	v_lshl_add_u64 v[210:211], v[58:59], 0, s[0:1]
	v_lshl_add_u64 v[210:211], v[210:211], 0, s[40:41]
	v_lshl_add_u64 v[214:215], v[58:59], 0, s[0:1]
	v_lshl_add_u64 v[214:215], v[214:215], 0, s[44:45]
	v_lshl_add_u64 v[218:219], v[58:59], 0, s[0:1]
	v_lshl_add_u64 v[218:219], v[218:219], 0, s[46:47]
	v_lshl_add_u64 v[226:227], v[58:59], 0, s[0:1]
	v_lshl_add_u64 v[230:231], v[58:59], 0, s[0:1]
	v_add_co_u32_e32 v230, vcc, s6, v230
	s_nop 1
	v_addc_co_u32_e32 v231, vcc, 0, v231, vcc
	v_lshl_add_u64 v[234:235], v[58:59], 0, s[0:1]
	v_add_co_u32_e32 v234, vcc, s7, v234
	s_nop 1
	v_addc_co_u32_e32 v235, vcc, 0, v235, vcc
	v_lshl_add_u64 v[238:239], v[58:59], 0, s[0:1]
	v_add_co_u32_e32 v238, vcc, s8, v238
	s_nop 1
	v_addc_co_u32_e32 v239, vcc, 0, v239, vcc
	global_load_dwordx4 v[206:209], v[206:207], off offset:16
	global_load_dwordx4 v[210:213], v[210:211], off offset:16
	global_load_dwordx4 v[214:217], v[214:215], off offset:16
	global_load_dwordx4 v[218:221], v[218:219], off offset:16
	global_load_dwordx4 v[222:225], v[60:61], off offset:16
	global_load_dwordx4 v[226:229], v[226:227], off
	global_load_dwordx4 v[230:233], v[230:231], off
	global_load_dwordx4 v[234:237], v[234:235], off
	global_load_dwordx4 v[238:241], v[238:239], off
	global_load_dwordx4 v[242:245], v[60:61], off
	s_waitcnt vmcnt(0)
	v_pk_add_f32 v[206:207], v[206:207], 0 op_sel_hi:[1,0]
	s_nop 0
	v_pk_add_f32 v[206:207], v[206:207], v[210:211]
	v_pk_add_f32 v[206:207], v[206:207], v[214:215]
	v_pk_add_f32 v[206:207], v[206:207], v[218:219]
	v_pk_mul_f32 v[222:223], v[222:223], 0.5 op_sel_hi:[1,0]
	s_nop 0
	v_pk_fma_f32 v[112:113], v[206:207], v[222:223], v[112:113]
	v_pk_add_f32 v[226:227], v[226:227], 0 op_sel_hi:[1,0]
	s_nop 0
	v_pk_add_f32 v[226:227], v[226:227], v[230:231]
	v_pk_add_f32 v[226:227], v[226:227], v[234:235]
	v_pk_add_f32 v[226:227], v[226:227], v[238:239]
	v_pk_mul_f32 v[242:243], v[242:243], 0.5 op_sel_hi:[1,0]
	s_nop 0
	v_pk_fma_f32 v[108:109], v[226:227], v[242:243], v[108:109]
	v_pk_add_f32 v[228:229], v[228:229], 0 op_sel_hi:[1,0]
	s_nop 0
	v_pk_add_f32 v[228:229], v[228:229], v[232:233]
	v_pk_add_f32 v[228:229], v[228:229], v[236:237]
	v_pk_add_f32 v[228:229], v[228:229], v[240:241]
	v_pk_mul_f32 v[244:245], v[244:245], 0.5 op_sel_hi:[1,0]
	s_nop 0
	v_pk_fma_f32 v[110:111], v[228:229], v[244:245], v[110:111]
	v_pk_add_f32 v[208:209], v[208:209], 0 op_sel_hi:[1,0]
	s_nop 0
	v_pk_add_f32 v[208:209], v[208:209], v[212:213]
	v_pk_add_f32 v[208:209], v[208:209], v[216:217]
	v_pk_add_f32 v[208:209], v[208:209], v[220:221]
	v_pk_mul_f32 v[224:225], v[224:225], 0.5 op_sel_hi:[1,0]
	s_nop 0
	v_pk_fma_f32 v[114:115], v[208:209], v[224:225], v[114:115]
	v_lshl_add_u64 v[206:207], v[72:73], 0, s[0:1]
	v_lshl_add_u64 v[210:211], v[72:73], 0, s[0:1]
	v_lshl_add_u64 v[210:211], v[210:211], 0, s[40:41]
	v_lshl_add_u64 v[214:215], v[72:73], 0, s[0:1]
	v_lshl_add_u64 v[214:215], v[214:215], 0, s[44:45]
	v_lshl_add_u64 v[218:219], v[72:73], 0, s[0:1]
	v_lshl_add_u64 v[218:219], v[218:219], 0, s[46:47]
	v_lshl_add_u64 v[226:227], v[72:73], 0, s[0:1]
	v_lshl_add_u64 v[230:231], v[72:73], 0, s[0:1]
	v_add_co_u32_e32 v230, vcc, s6, v230
	s_nop 1
	v_addc_co_u32_e32 v231, vcc, 0, v231, vcc
	v_lshl_add_u64 v[234:235], v[72:73], 0, s[0:1]
	v_add_co_u32_e32 v234, vcc, s7, v234
	s_nop 1
	v_addc_co_u32_e32 v235, vcc, 0, v235, vcc
	v_lshl_add_u64 v[238:239], v[72:73], 0, s[0:1]
	v_add_co_u32_e32 v238, vcc, s8, v238
	s_nop 1
	v_addc_co_u32_e32 v239, vcc, 0, v239, vcc
	global_load_dwordx4 v[206:209], v[206:207], off offset:16
	global_load_dwordx4 v[210:213], v[210:211], off offset:16
	global_load_dwordx4 v[214:217], v[214:215], off offset:16
	global_load_dwordx4 v[218:221], v[218:219], off offset:16
	global_load_dwordx4 v[222:225], v[62:63], off offset:16
	global_load_dwordx4 v[226:229], v[226:227], off
	global_load_dwordx4 v[230:233], v[230:231], off
	global_load_dwordx4 v[234:237], v[234:235], off
	global_load_dwordx4 v[238:241], v[238:239], off
	global_load_dwordx4 v[242:245], v[62:63], off
	s_waitcnt vmcnt(0)
; #define GAS __attribute__((address_space(1)))
; __device__ __forceinline__ void norm_phase(bool from_input, int gw, int NGW, int lane_in, float* H, const float* x_in, const float* c_in, const float* gain, const float* modL, int js, int jc, bf16* XN, ...
;     ...
;             for (int j = 0; j < 4; ++j) { const int c0 = 8 * (lane + 64 * j); f32x4 a0 = {0.f, 0.f, 0.f, 0.f}, a1 = a0;
;                 for (int qs = 0; qs < nsl; ++qs) { const GAS f32x4* sp = (const GAS f32x4*)(SLAB + ((size_t)qs * 512 + b * 256 + s) * 2048 + c0); a0 += sp[0]; a1 += sp[1]; }
;                 const f32x4 g0 = *(const f32x4*)(sgate + c0) * scoef, g1 = *(const f32x4*)(sgate + c0 + 4) * scoef;
; #pragma unroll
;                 for (int q = 0; q < 4; ++q) { v[j][q] += g0[q] * a0[q]; v[j][4 + q] += g1[q] * a1[q]; } }
	v_pk_add_f32 v[206:207], v[206:207], 0 op_sel_hi:[1,0]
	s_nop 0
	v_pk_add_f32 v[206:207], v[206:207], v[210:211]
	v_pk_add_f32 v[206:207], v[206:207], v[214:215]
	v_pk_add_f32 v[206:207], v[206:207], v[218:219]
	v_pk_mul_f32 v[222:223], v[222:223], 0.5 op_sel_hi:[1,0]
	s_nop 0
	v_pk_fma_f32 v[120:121], v[206:207], v[222:223], v[120:121]
	v_pk_add_f32 v[226:227], v[226:227], 0 op_sel_hi:[1,0]
	s_nop 0
	v_pk_add_f32 v[226:227], v[226:227], v[230:231]
	v_pk_add_f32 v[226:227], v[226:227], v[234:235]
	v_pk_add_f32 v[226:227], v[226:227], v[238:239]
	v_pk_mul_f32 v[242:243], v[242:243], 0.5 op_sel_hi:[1,0]
	s_nop 0
	v_pk_fma_f32 v[116:117], v[226:227], v[242:243], v[116:117]
	v_pk_add_f32 v[228:229], v[228:229], 0 op_sel_hi:[1,0]
	s_nop 0
	v_pk_add_f32 v[228:229], v[228:229], v[232:233]
	v_pk_add_f32 v[228:229], v[228:229], v[236:237]
	v_pk_add_f32 v[228:229], v[228:229], v[240:241]
	v_pk_mul_f32 v[244:245], v[244:245], 0.5 op_sel_hi:[1,0]
	s_nop 0
	v_pk_fma_f32 v[118:119], v[228:229], v[244:245], v[118:119]
	v_pk_add_f32 v[208:209], v[208:209], 0 op_sel_hi:[1,0]
	s_nop 0
	v_pk_add_f32 v[208:209], v[208:209], v[212:213]
	v_pk_add_f32 v[208:209], v[208:209], v[216:217]
	v_pk_add_f32 v[208:209], v[208:209], v[220:221]
	v_pk_mul_f32 v[224:225], v[224:225], 0.5 op_sel_hi:[1,0]
	s_nop 0
	v_pk_fma_f32 v[122:123], v[208:209], v[224:225], v[122:123]
	v_lshl_add_u64 v[206:207], v[64:65], 0, s[0:1]
	v_lshl_add_u64 v[210:211], v[64:65], 0, s[0:1]
	v_add_co_u32_e32 v210, vcc, s6, v210
	s_nop 1
	v_addc_co_u32_e32 v211, vcc, 0, v211, vcc
	v_lshl_add_u64 v[214:215], v[64:65], 0, s[0:1]
	v_add_co_u32_e32 v214, vcc, s7, v214
	s_nop 1
	v_addc_co_u32_e32 v215, vcc, 0, v215, vcc
	v_lshl_add_u64 v[218:219], v[64:65], 0, s[0:1]
	v_add_co_u32_e32 v218, vcc, s8, v218
	s_nop 1
	v_addc_co_u32_e32 v219, vcc, 0, v219, vcc
	v_lshl_add_u64 v[226:227], v[64:65], 0, s[0:1]
	v_lshl_add_u64 v[230:231], v[64:65], 0, s[0:1]
	v_lshl_add_u64 v[230:231], v[230:231], 0, s[40:41]
	v_lshl_add_u64 v[234:235], v[64:65], 0, s[0:1]
	v_lshl_add_u64 v[234:235], v[234:235], 0, s[44:45]
	v_lshl_add_u64 v[238:239], v[64:65], 0, s[0:1]
	v_lshl_add_u64 v[238:239], v[238:239], 0, s[46:47]
	global_load_dwordx4 v[206:209], v[206:207], off
	global_load_dwordx4 v[210:213], v[210:211], off
	global_load_dwordx4 v[214:217], v[214:215], off
	global_load_dwordx4 v[218:221], v[218:219], off
	global_load_dwordx4 v[222:225], v[66:67], off
	global_load_dwordx4 v[226:229], v[226:227], off offset:16
	global_load_dwordx4 v[230:233], v[230:231], off offset:16
	global_load_dwordx4 v[234:237], v[234:235], off offset:16
	global_load_dwordx4 v[238:241], v[238:239], off offset:16
	global_load_dwordx4 v[242:245], v[66:67], off offset:16
	s_waitcnt vmcnt(0)
	v_pk_add_f32 v[206:207], v[206:207], 0 op_sel_hi:[1,0]
	s_nop 0
	v_pk_add_f32 v[206:207], v[206:207], v[210:211]
	v_pk_add_f32 v[206:207], v[206:207], v[214:215]
	v_pk_add_f32 v[206:207], v[206:207], v[218:219]
	v_pk_mul_f32 v[222:223], v[222:223], 0.5 op_sel_hi:[1,0]
	s_nop 0
	v_pk_fma_f32 v[128:129], v[206:207], v[222:223], v[128:129]
	v_pk_add_f32 v[226:227], v[226:227], 0 op_sel_hi:[1,0]
	s_nop 0
	v_pk_add_f32 v[226:227], v[226:227], v[230:231]
	v_pk_add_f32 v[226:227], v[226:227], v[234:235]
	v_pk_add_f32 v[226:227], v[226:227], v[238:239]
	v_pk_mul_f32 v[242:243], v[242:243], 0.5 op_sel_hi:[1,0]
	s_nop 0
	v_pk_fma_f32 v[132:133], v[226:227], v[242:243], v[132:133]
	v_pk_add_f32 v[208:209], v[208:209], 0 op_sel_hi:[1,0]
	s_nop 0
	v_pk_add_f32 v[208:209], v[208:209], v[212:213]
	v_pk_add_f32 v[208:209], v[208:209], v[216:217]
	v_pk_add_f32 v[208:209], v[208:209], v[220:221]
	v_pk_mul_f32 v[224:225], v[224:225], 0.5 op_sel_hi:[1,0]
	s_nop 0
	v_pk_fma_f32 v[130:131], v[208:209], v[224:225], v[130:131]
	v_pk_add_f32 v[228:229], v[228:229], 0 op_sel_hi:[1,0]
	s_nop 0
	v_pk_add_f32 v[228:229], v[228:229], v[232:233]
	v_pk_add_f32 v[228:229], v[228:229], v[236:237]
	v_pk_add_f32 v[228:229], v[228:229], v[240:241]
	v_pk_mul_f32 v[244:245], v[244:245], 0.5 op_sel_hi:[1,0]
	s_nop 0
	v_pk_fma_f32 v[134:135], v[228:229], v[244:245], v[134:135]
	v_lshl_add_u64 v[206:207], v[68:69], 0, s[0:1]
	v_lshl_add_u64 v[210:211], v[68:69], 0, s[0:1]
	v_lshl_add_u64 v[210:211], v[210:211], 0, s[40:41]
	v_lshl_add_u64 v[214:215], v[68:69], 0, s[0:1]
	v_lshl_add_u64 v[214:215], v[214:215], 0, s[44:45]
	v_lshl_add_u64 v[218:219], v[68:69], 0, s[0:1]
	v_lshl_add_u64 v[218:219], v[218:219], 0, s[46:47]
	v_lshl_add_u64 v[226:227], v[68:69], 0, s[0:1]
	v_lshl_add_u64 v[230:231], v[68:69], 0, s[0:1]
	v_add_co_u32_e32 v230, vcc, s6, v230
	s_nop 1
	v_addc_co_u32_e32 v231, vcc, 0, v231, vcc
	v_lshl_add_u64 v[234:235], v[68:69], 0, s[0:1]
	v_add_co_u32_e32 v234, vcc, s7, v234
	s_nop 1
	v_addc_co_u32_e32 v235, vcc, 0, v235, vcc
	v_lshl_add_u64 v[238:239], v[68:69], 0, s[0:1]
	v_add_co_u32_e32 v238, vcc, s8, v238
	s_nop 1
	v_addc_co_u32_e32 v239, vcc, 0, v239, vcc
	global_load_dwordx4 v[206:209], v[206:207], off offset:16
	global_load_dwordx4 v[210:213], v[210:211], off offset:16
	global_load_dwordx4 v[214:217], v[214:215], off offset:16
	global_load_dwordx4 v[218:221], v[218:219], off offset:16
	global_load_dwordx4 v[222:225], v[70:71], off offset:16
	global_load_dwordx4 v[226:229], v[226:227], off
	global_load_dwordx4 v[230:233], v[230:231], off
	global_load_dwordx4 v[234:237], v[234:235], off
	global_load_dwordx4 v[238:241], v[238:239], off
	global_load_dwordx4 v[242:245], v[70:71], off
	s_waitcnt vmcnt(0)
; #define GAS __attribute__((address_space(1)))
; __device__ __forceinline__ void h24_store(unsigned char* Hb, size_t r, int lane, const float (&v)[4][8]) {
; #pragma unroll
;     for (int j = 0; j < 4; ++j) { const size_t e = r * 2048 + 8 * (lane + 64 * j); unsigned u[8];
; #pragma unroll
;         for (int q = 0; q < 8; ++q) u[q] = __builtin_bit_cast(unsigned, v[j][q]) + 0x800u;
;         v4u hi; unsigned lo = 0u;
; #pragma unroll
;         for (int q = 0; q < 4; ++q) hi[q] = (u[2 * q] >> 16) | (u[2 * q + 1] & 0xffff0000u);
; #pragma unroll
;         for (int q = 0; q < 8; ++q) lo |= ((u[q] >> 12) & 0xfu) << (4 * q);
;         __builtin_nontemporal_store(hi, (GAS v4u*)(Hb + e * 2)); __builtin_nontemporal_store(lo, (GAS unsigned*)(Hb + H_LO_OFF + (e >> 1))); }
; __device__ __forceinline__ void norm_phase(bool from_input, int gw, int NGW, int lane_in, float* H, const float* x_in, const float* c_in, const float* gain, const float* modL, int js, int jc, bf16* XN, ...
;     ...
;             for (int j = 0; j < 4; ++j) { const int c0 = 8 * (lane + 64 * j); f32x4 a0 = {0.f, 0.f, 0.f, 0.f}, a1 = a0;
;                 for (int qs = 0; qs < nsl; ++qs) { const GAS f32x4* sp = (const GAS f32x4*)(SLAB + ((size_t)qs * 512 + b * 256 + s) * 2048 + c0); a0 += sp[0]; a1 += sp[1]; }
;                 const f32x4 g0 = *(const f32x4*)(sgate + c0) * scoef, g1 = *(const f32x4*)(sgate + c0 + 4) * scoef;
; #pragma unroll
;                 for (int q = 0; q < 4; ++q) { v[j][q] += g0[q] * a0[q]; v[j][4 + q] += g1[q] * a1[q]; } }
;             h24_store(Hb, (size_t)r, lane, v);
	v_pk_add_f32 v[206:207], v[206:207], 0 op_sel_hi:[1,0]
	s_nop 0
	v_pk_add_f32 v[206:207], v[206:207], v[210:211]
	v_pk_add_f32 v[206:207], v[206:207], v[214:215]
	v_pk_add_f32 v[206:207], v[206:207], v[218:219]
	v_pk_mul_f32 v[222:223], v[222:223], 0.5 op_sel_hi:[1,0]
	s_nop 0
	v_pk_fma_f32 v[152:153], v[206:207], v[222:223], v[152:153]
	v_pk_add_f32 v[226:227], v[226:227], 0 op_sel_hi:[1,0]
	s_nop 0
	v_pk_add_f32 v[226:227], v[226:227], v[230:231]
	v_pk_add_f32 v[226:227], v[226:227], v[234:235]
	v_pk_add_f32 v[226:227], v[226:227], v[238:239]
	v_pk_mul_f32 v[242:243], v[242:243], 0.5 op_sel_hi:[1,0]
	s_nop 0
	v_pk_fma_f32 v[148:149], v[226:227], v[242:243], v[148:149]
	v_pk_add_f32 v[228:229], v[228:229], 0 op_sel_hi:[1,0]
	s_nop 0
	v_pk_add_f32 v[228:229], v[228:229], v[232:233]
	v_pk_add_f32 v[228:229], v[228:229], v[236:237]
	v_pk_add_f32 v[228:229], v[228:229], v[240:241]
	v_pk_mul_f32 v[244:245], v[244:245], 0.5 op_sel_hi:[1,0]
	s_nop 0
	v_pk_fma_f32 v[150:151], v[228:229], v[244:245], v[150:151]
	v_pk_add_f32 v[208:209], v[208:209], 0 op_sel_hi:[1,0]
	s_nop 0
	v_pk_add_f32 v[208:209], v[208:209], v[212:213]
	v_pk_add_f32 v[208:209], v[208:209], v[216:217]
	v_pk_add_f32 v[208:209], v[208:209], v[220:221]
	v_pk_mul_f32 v[224:225], v[224:225], 0.5 op_sel_hi:[1,0]
	s_nop 0
	v_pk_fma_f32 v[154:155], v[208:209], v[224:225], v[154:155]
	v_add_u32_e32 v47, 0x800, v112
	v_add_u32_e32 v45, 0x800, v114
	v_add_u32_e32 v36, 0x800, v110
	v_add_u32_e32 v37, 0x800, v108
	v_add_u32_e32 v38, 0x800, v111
	v_add_u32_e32 v39, 0x800, v109
	v_lshrrev_b32_e32 v32, 16, v36
	v_lshrrev_b32_e32 v34, 16, v37
	v_add_u32_e32 v157, 0x800, v113
	v_lshrrev_b32_e32 v158, 16, v47
	v_and_or_b32 v33, v38, s4, v32
	v_and_or_b32 v32, v39, s4, v34
	v_lshrrev_b32_e32 v37, 12, v37
	v_lshrrev_b32_e32 v39, 8, v39
	v_lshrrev_b32_e32 v36, 4, v36
	v_and_b32_e32 v38, 0xf000, v38
	v_add_u32_e32 v156, 0x800, v115
	v_lshrrev_b32_e32 v35, 16, v45
	v_and_or_b32 v34, v157, s4, v158
	v_and_b32_e32 v39, 0xf0, v39
	v_and_b32_e32 v36, 0xf00, v36
	v_lshlrev_b32_e32 v47, 4, v47
	v_lshlrev_b32_e32 v157, 8, v157
	v_and_or_b32 v37, v37, 15, v38
	v_and_or_b32 v35, v156, s4, v35
	v_and_b32_e32 v47, 0xf0000, v47
	v_and_b32_e32 v157, 0xf00000, v157
	v_lshlrev_b32_e32 v45, 12, v45
	v_lshlrev_b32_e32 v156, 16, v156
	v_or3_b32 v36, v37, v39, v36
	v_and_b32_e32 v45, 0xf000000, v45
	v_and_b32_e32 v156, 0xf0000000, v156
	v_or3_b32 v36, v36, v47, v157
	v_or3_b32 v36, v36, v45, v156
	global_store_dwordx4 v[124:125], v[32:35], off nt
	global_store_dword v[126:127], v36, off nt
	v_add_u32_e32 v36, 0x800, v118
	v_add_u32_e32 v37, 0x800, v116
	v_add_u32_e32 v38, 0x800, v119
	v_add_u32_e32 v39, 0x800, v117
	v_add_u32_e32 v47, 0x800, v120
	v_lshrrev_b32_e32 v32, 16, v36
	v_lshrrev_b32_e32 v34, 16, v37
	v_add_u32_e32 v45, 0x800, v122
	v_add_u32_e32 v125, 0x800, v121
	v_lshrrev_b32_e32 v126, 16, v47
	v_and_or_b32 v33, v38, s4, v32
	v_and_or_b32 v32, v39, s4, v34
	v_lshrrev_b32_e32 v37, 12, v37
	v_lshrrev_b32_e32 v39, 8, v39
	v_lshrrev_b32_e32 v36, 4, v36
	v_and_b32_e32 v38, 0xf000, v38
	v_add_u32_e32 v124, 0x800, v123
	v_lshrrev_b32_e32 v35, 16, v45
	v_and_or_b32 v34, v125, s4, v126
	v_and_b32_e32 v39, 0xf0, v39
	v_and_b32_e32 v36, 0xf00, v36
	v_lshlrev_b32_e32 v47, 4, v47
	v_lshlrev_b32_e32 v125, 8, v125
	v_and_or_b32 v37, v37, 15, v38
	v_and_or_b32 v35, v124, s4, v35
	v_and_b32_e32 v47, 0xf0000, v47
	v_and_b32_e32 v125, 0xf00000, v125
	v_lshlrev_b32_e32 v45, 12, v45
	v_lshlrev_b32_e32 v124, 16, v124
	v_or3_b32 v36, v37, v39, v36
	v_and_b32_e32 v45, 0xf000000, v45
	v_and_b32_e32 v124, 0xf0000000, v124
	v_or3_b32 v36, v36, v47, v125
	v_or3_b32 v36, v36, v45, v124
	global_store_dwordx4 v[136:137], v[32:35], off nt
	global_store_dword v[138:139], v36, off nt
	v_add_u32_e32 v36, 0x800, v130
	v_add_u32_e32 v37, 0x800, v128
	v_add_u32_e32 v38, 0x800, v131
	v_add_u32_e32 v39, 0x800, v129
	v_add_u32_e32 v47, 0x800, v132
	v_lshrrev_b32_e32 v32, 16, v36
	v_lshrrev_b32_e32 v34, 16, v37
	v_add_u32_e32 v45, 0x800, v134
	v_add_u32_e32 v125, 0x800, v133
	v_lshrrev_b32_e32 v126, 16, v47
	v_and_or_b32 v33, v38, s4, v32
	v_and_or_b32 v32, v39, s4, v34
	v_lshrrev_b32_e32 v37, 12, v37
	v_lshrrev_b32_e32 v39, 8, v39
	v_lshrrev_b32_e32 v36, 4, v36
	v_and_b32_e32 v38, 0xf000, v38
	v_add_u32_e32 v124, 0x800, v135
	v_lshrrev_b32_e32 v35, 16, v45
	v_and_or_b32 v34, v125, s4, v126
	v_and_b32_e32 v39, 0xf0, v39
	v_and_b32_e32 v36, 0xf00, v36
	v_lshlrev_b32_e32 v47, 4, v47
	v_lshlrev_b32_e32 v125, 8, v125
	v_and_or_b32 v37, v37, 15, v38
	v_and_or_b32 v35, v124, s4, v35
	v_and_b32_e32 v47, 0xf0000, v47
	v_and_b32_e32 v125, 0xf00000, v125
	v_lshlrev_b32_e32 v45, 12, v45
	v_lshlrev_b32_e32 v124, 16, v124
	v_or3_b32 v36, v37, v39, v36
	v_and_b32_e32 v45, 0xf000000, v45
	v_and_b32_e32 v124, 0xf0000000, v124
	v_or3_b32 v36, v36, v47, v125
	v_or3_b32 v36, v36, v45, v124
	global_store_dwordx4 v[140:141], v[32:35], off nt
	global_store_dword v[142:143], v36, off nt
	v_add_u32_e32 v36, 0x800, v150
	v_add_u32_e32 v37, 0x800, v148
	v_add_u32_e32 v38, 0x800, v151
	v_add_u32_e32 v39, 0x800, v149
	v_add_u32_e32 v47, 0x800, v152
	v_lshrrev_b32_e32 v32, 16, v36
	v_lshrrev_b32_e32 v34, 16, v37
	v_add_u32_e32 v45, 0x800, v154
	v_add_u32_e32 v125, 0x800, v153
	v_lshrrev_b32_e32 v126, 16, v47
	v_and_or_b32 v33, v38, s4, v32
	v_and_or_b32 v32, v39, s4, v34
	v_lshrrev_b32_e32 v37, 12, v37
	v_lshrrev_b32_e32 v39, 8, v39
	v_lshrrev_b32_e32 v36, 4, v36
	v_and_b32_e32 v38, 0xf000, v38
	v_add_u32_e32 v124, 0x800, v155
	v_lshrrev_b32_e32 v35, 16, v45
	v_and_or_b32 v34, v125, s4, v126
	v_and_b32_e32 v39, 0xf0, v39
	v_and_b32_e32 v36, 0xf00, v36
	v_lshlrev_b32_e32 v47, 4, v47
	v_lshlrev_b32_e32 v125, 8, v125
	v_and_or_b32 v37, v37, 15, v38
	v_and_or_b32 v35, v124, s4, v35
	v_and_b32_e32 v47, 0xf0000, v47
	v_and_b32_e32 v125, 0xf00000, v125
	v_lshlrev_b32_e32 v45, 12, v45
	v_lshlrev_b32_e32 v124, 16, v124
	v_or3_b32 v36, v37, v39, v36
	v_and_b32_e32 v45, 0xf000000, v45
	v_and_b32_e32 v124, 0xf0000000, v124
	v_or3_b32 v36, v36, v47, v125
	v_or3_b32 v36, v36, v45, v124
	global_store_dwordx4 v[144:145], v[32:35], off nt
	global_store_dword v[146:147], v36, off nt
	s_branch .LBB0_1829
